# phase-output stores of attention, out-proj and PEER-topk phases written through (sc0 sc1) so the grid barriers L2 write-back is cheaper
# speedup vs baseline: 1.0170x; 1.0052x over previous
;     static __device__ __forceinline__ unsigned pk8(float x0, float x1, float x2, float x3) { int w = 0; w = __builtin_amdgcn_cvt_pk_fp8_f32(x0, x1, w, false); w = __builtin_amdgcn_cvt_pk_fp8_f32(x2, x3, w, true); return (unsigned)w; }
; __device__ __forceinline__ void attn_unit_f8(const UnitDesc8& U, char* shm) {
;     ...
;     if (kw) { glds16s(dsrc, dvoff, (unsigned)__builtin_amdgcn_readfirstlane(ddst)); glds16s(dsrc + TS, dvoff, (unsigned)__builtin_amdgcn_readfirstlane(ddst + TS)); glds16s(dsrc + 2 * TS, dvoff, (unsigned)__builtin_amdgcn_readfirstlane(ddst + 2 * TS)); }
;     else { glds16s(dsrc, dvoff, (unsigned)__builtin_amdgcn_readfirstlane(ddst)); glds16s(dsrc + TS, dvoff, (unsigned)__builtin_amdgcn_readfirstlane(ddst + TS)); }
;     WB(2);
;     FRAG(kf[0], LDS_K); FRAG(kf[1], LDS_K + 2048);
;     p0 = MFQK(kf[0]); p1 = MFQK(kf[1]);
; #pragma unroll
;     for (int r = 0; r < 16; ++r) p0[r] = EX(p0[r]);
; #pragma unroll
;     for (int r = 0; r < 4; ++r) p1[r] = EX(p1[r]);
; #pragma unroll
;     for (int w = 0; w < 3; ++w) pfA[w] = pk8(pfA[w], p0[4 * w], p0[4 * w + 1], p0[4 * w + 2], p0[4 * w + 3]);
;     WB(0);
;     DMA8(0, kw ? 3 : 2);
;     FRAG(kf[0], LDS_K + TS); FRAG(kf[1], LDS_K + TS + 2048);
;     WB(1);
;     for (int t = 1; t <= NT - 4; t += 4) {
;         STEP_F8(pb0, pb1, p0, p1, pfB, pfA, t, true, true, true, 2, 0, 0, 3);     WB(1);
;         STEP_F8(p0, p1, pb0, pb1, pfA, pfB, t + 1, true, true, true, 3, 1, 1, 0); WB(1);
;         STEP_F8(pb0, pb1, p0, p1, pfB, pfA, t + 2, true, true, true, 0, 2, 2, 1); WB(1);
;         STEP_F8(p0, p1, pb0, pb1, pfA, pfB, t + 3, true, true, true, 1, 3, 3, 2); WB(1);
;     }
;     STEP_F8(pb0, pb1, p0, p1, pfB, pfA, NT - 3, false, true, true, 2, 0, 0, 3);   WB(0);
;     STEP_F8(p0, p1, pb0, pb1, pfA, pfB, NT - 2, false, false, true, 3, 1, 1, 0);  WB(0);
;     STEP_F8(pb0, pb1, p0, p1, pfB, pfA, NT - 1, false, false, false, 0, 2, 2, 1); WB(0);
; #pragma unroll
;     for (int r = 4; r < 16; ++r) pb1[r] = EX(pb1[r]);
;     pfB[3] = pk8(pfB[3], pb0[12], pb0[13], pb0[14], pb0[15]);
; #pragma unroll
;     for (int w = 0; w < 4; ++w) pfB[4 + w] = pk8(pfB[4 + w], pb1[4 * w], pb1[4 * w + 1], pb1[4 * w + 2], pb1[4 * w + 3]);
;     FRAG(vf[0], LDS_V + 3 * TS); FRAG(vf[1], LDS_V + 3 * TS + 2048);
;     o[0] = MFPV(pfB, vf[0], o[0]); o[1] = MFPV(pfB, vf[1], o[1]); ls = MFPV(pfB, ones8, ls);
.LBB0_442:
	s_waitcnt lgkmcnt(5)
	v_mfma_scale_f32_32x32x64_f8f6f4 v[66:81], v[106:113], v[132:139], v[18:33], v198, v197 op_sel_hi:[0,0,0]
	ds_read_b128 v[82:85], v201 offset:8192
	ds_read_b128 v[90:93], v201 offset:10240
	ds_read_b128 v[86:89], v202 offset:8192
	ds_read_b128 v[94:97], v202 offset:10240
	s_lshl_b64 s[0:1], s[0:1], 11
	s_add_u32 s0, s94, s0
	s_addc_u32 s1, s95, s1
	s_lshl_b32 s10, s62, 7
	s_add_u32 s0, s0, s10
	s_addc_u32 s1, s1, 0
	s_waitcnt lgkmcnt(8)
	v_mfma_scale_f32_32x32x64_f8f6f4 v[98:113], v[98:105], v[132:139], v[18:33], v198, v197 op_sel_hi:[0,0,0]
	s_nop 7
	v_exp_f32_e32 v66, v66
	v_exp_f32_e32 v67, v67
	v_exp_f32_e32 v68, v68
	v_exp_f32_e32 v69, v69
	v_exp_f32_e32 v70, v70
	v_exp_f32_e32 v71, v71
	v_exp_f32_e32 v72, v72
	s_nop 0
	v_cvt_pk_fp8_f32 v140, v66, v67
	v_exp_f32_e32 v73, v73
	v_exp_f32_e32 v74, v74
	v_exp_f32_e32 v75, v75
	v_exp_f32_e32 v76, v76
	v_exp_f32_e32 v77, v77
	v_exp_f32_e32 v78, v78
	v_exp_f32_e32 v79, v79
	v_cvt_pk_fp8_f32 v140, v68, v69 op_sel:[0,0,1]
	s_nop 0
	s_nop 0
	v_cvt_pk_fp8_f32 v141, v70, v71
	v_cvt_pk_fp8_f32 v142, v74, v75
	v_exp_f32_e32 v80, v80
	v_exp_f32_e32 v81, v81
	v_exp_f32_e32 v98, v98
	v_exp_f32_e32 v99, v99
	v_exp_f32_e32 v100, v100
	v_exp_f32_e32 v101, v101
	v_cvt_pk_fp8_f32 v141, v72, v73 op_sel:[0,0,1]
	v_cvt_pk_fp8_f32 v142, v76, v77 op_sel:[0,0,1]
	s_nop 0
	s_waitcnt vmcnt(0) lgkmcnt(0)
	s_barrier
	ds_read_b128 v[164:167], v201 offset:20480
	ds_read_b128 v[172:175], v201 offset:22528
	ds_read_b128 v[168:171], v202 offset:20480
	ds_read_b128 v[176:179], v202 offset:22528
	v_cvt_pk_fp8_f32 v143, v78, v79
	v_exp_f32_e32 v102, v102
	v_exp_f32_e32 v103, v103
	v_exp_f32_e32 v104, v104
	v_exp_f32_e32 v105, v105
	v_exp_f32_e32 v106, v106
	v_exp_f32_e32 v107, v107
	v_cvt_pk_fp8_f32 v143, v80, v81 op_sel:[0,0,1]
	s_waitcnt lgkmcnt(5)
	v_mfma_scale_f32_32x32x64_f8f6f4 v[66:81], v[82:89], v[132:139], v[18:33], v198, v197 op_sel_hi:[0,0,0]
	s_nop 0
	v_cvt_pk_fp8_f32 v144, v98, v99
	v_cvt_pk_fp8_f32 v145, v102, v103
	v_exp_f32_e32 v108, v108
	v_exp_f32_e32 v109, v109
	v_exp_f32_e32 v110, v110
	v_exp_f32_e32 v111, v111
	v_exp_f32_e32 v112, v112
	v_exp_f32_e32 v113, v113
	v_cvt_pk_fp8_f32 v144, v100, v101 op_sel:[0,0,1]
	v_cvt_pk_fp8_f32 v145, v104, v105 op_sel:[0,0,1]
	s_waitcnt lgkmcnt(4)
	v_mfma_scale_f32_32x32x64_f8f6f4 v[82:97], v[90:97], v[132:139], v[18:33], v198, v197 op_sel_hi:[0,0,0]
	s_nop 0
	v_cvt_pk_fp8_f32 v146, v106, v107
	v_cvt_pk_fp8_f32 v147, v110, v111
	v_cvt_pk_fp8_f32 v146, v108, v109 op_sel:[0,0,1]
	v_cvt_pk_fp8_f32 v147, v112, v113 op_sel:[0,0,1]
	s_nop 0
	ds_read_b128 v[208:211], v201 offset:12288
	ds_read_b128 v[216:219], v201 offset:14336
	ds_read_b128 v[212:215], v202 offset:12288
	ds_read_b128 v[220:223], v202 offset:14336
	v_exp_f32_e32 v66, v66
	v_exp_f32_e32 v67, v67
	v_exp_f32_e32 v68, v68
	v_exp_f32_e32 v69, v69
	v_exp_f32_e32 v70, v70
	v_exp_f32_e32 v71, v71
	v_exp_f32_e32 v72, v72
	v_mov_b32_e32 v1, v124
	v_cvt_pk_fp8_f32 v1, v66, v67
	v_mov_b64_e32 v[98:99], v[124:125]
	v_exp_f32_e32 v73, v73
	v_exp_f32_e32 v74, v74
	v_cvt_pk_fp8_f32 v1, v68, v69 op_sel:[0,0,1]
	v_exp_f32_e32 v75, v75
	v_exp_f32_e32 v76, v76
	v_exp_f32_e32 v77, v77
	v_exp_f32_e32 v78, v78
	v_exp_f32_e32 v79, v79
	v_mov_b64_e32 v[100:101], v[126:127]
	v_mov_b64_e32 v[102:103], v[128:129]
	v_mov_b64_e32 v[104:105], v[130:131]
	v_mov_b32_e32 v98, v1
	s_nop 0
	v_cvt_pk_fp8_f32 v99, v70, v71
	v_cvt_pk_fp8_f32 v100, v74, v75
	v_exp_f32_e32 v80, v80
	v_exp_f32_e32 v81, v81
	v_exp_f32_e32 v82, v82
	v_exp_f32_e32 v83, v83
	v_exp_f32_e32 v84, v84
	v_exp_f32_e32 v85, v85
	v_cvt_pk_fp8_f32 v99, v72, v73 op_sel:[0,0,1]
	v_cvt_pk_fp8_f32 v100, v76, v77 op_sel:[0,0,1]
	s_nop 0
	s_waitcnt vmcnt(0) lgkmcnt(0)
	s_barrier
	ds_read_b128 v[106:109], v201 offset:24576
	ds_read_b128 v[224:227], v201 offset:26624
	ds_read_b128 v[110:113], v202 offset:24576
	ds_read_b128 v[228:231], v202 offset:26624
	v_cvt_pk_fp8_f32 v101, v78, v79
	v_exp_f32_e32 v86, v86
	v_exp_f32_e32 v87, v87
	v_exp_f32_e32 v88, v88
	v_exp_f32_e32 v89, v89
	v_exp_f32_e32 v90, v90
	v_exp_f32_e32 v91, v91
	v_cvt_pk_fp8_f32 v101, v80, v81 op_sel:[0,0,1]
	s_waitcnt lgkmcnt(5)
	v_mfma_scale_f32_32x32x64_f8f6f4 v[66:81], v[208:215], v[132:139], v[18:33], v198, v197 op_sel_hi:[0,0,0]
	s_nop 0
	v_cvt_pk_fp8_f32 v102, v82, v83
	v_cvt_pk_fp8_f32 v103, v86, v87
	v_exp_f32_e32 v92, v92
	v_exp_f32_e32 v93, v93
	v_exp_f32_e32 v94, v94
	v_exp_f32_e32 v95, v95
	v_exp_f32_e32 v96, v96
	v_exp_f32_e32 v97, v97
	v_cvt_pk_fp8_f32 v102, v84, v85 op_sel:[0,0,1]
	v_cvt_pk_fp8_f32 v103, v88, v89 op_sel:[0,0,1]
	s_waitcnt lgkmcnt(4)
	v_mfma_scale_f32_32x32x64_f8f6f4 v[18:33], v[216:223], v[132:139], v[18:33], v198, v197 op_sel_hi:[0,0,0]
	s_nop 0
	v_cvt_pk_fp8_f32 v104, v90, v91
	v_cvt_pk_fp8_f32 v105, v94, v95
	v_cvt_pk_fp8_f32 v104, v92, v93 op_sel:[0,0,1]
	v_cvt_pk_fp8_f32 v105, v96, v97 op_sel:[0,0,1]
	s_nop 0
	v_exp_f32_e32 v66, v66
	v_exp_f32_e32 v67, v67
	v_exp_f32_e32 v68, v68
	v_exp_f32_e32 v69, v69
	v_exp_f32_e32 v70, v70
	v_exp_f32_e32 v71, v71
	v_exp_f32_e32 v72, v72
	v_mov_b32_e32 v1, v140
	v_cvt_pk_fp8_f32 v1, v66, v67
	v_mov_b64_e32 v[82:83], v[140:141]
	v_exp_f32_e32 v73, v73
	v_exp_f32_e32 v74, v74
	v_cvt_pk_fp8_f32 v1, v68, v69 op_sel:[0,0,1]
	v_exp_f32_e32 v75, v75
	v_exp_f32_e32 v76, v76
	v_exp_f32_e32 v77, v77
	v_exp_f32_e32 v78, v78
	v_exp_f32_e32 v79, v79
	v_mov_b64_e32 v[84:85], v[142:143]
	v_mov_b64_e32 v[86:87], v[144:145]
	v_mov_b64_e32 v[88:89], v[146:147]
	v_mov_b32_e32 v82, v1
	s_nop 0
	v_cvt_pk_fp8_f32 v83, v70, v71
	v_cvt_pk_fp8_f32 v84, v74, v75
	v_exp_f32_e32 v80, v80
	v_exp_f32_e32 v81, v81
	v_exp_f32_e32 v18, v18
	v_exp_f32_e32 v19, v19
	v_exp_f32_e32 v20, v20
	v_exp_f32_e32 v21, v21
	v_cvt_pk_fp8_f32 v83, v72, v73 op_sel:[0,0,1]
	v_cvt_pk_fp8_f32 v84, v76, v77 op_sel:[0,0,1]
	s_nop 0
	v_mfma_scale_f32_32x32x64_f8f6f4 v[2:17], v[124:131], v[116:123], v[2:17], v198, v198 op_sel_hi:[0,0,0]
	v_exp_f32_e32 v1, v22
	v_exp_f32_e32 v22, v23
	v_exp_f32_e32 v23, v24
	v_exp_f32_e32 v24, v25
	v_exp_f32_e32 v25, v26
	v_exp_f32_e32 v26, v27
	v_exp_f32_e32 v27, v28
	v_exp_f32_e32 v28, v29
	v_exp_f32_e32 v29, v30
	v_exp_f32_e32 v30, v31
	v_cvt_pk_fp8_f32 v85, v78, v79
	v_exp_f32_e32 v31, v32
	v_exp_f32_e32 v32, v33
	v_cvt_pk_fp8_f32 v86, v18, v19
	v_cvt_pk_fp8_f32 v87, v1, v22
	v_mfma_scale_f32_32x32x64_f8f6f4 v[50:65], v[124:131], v[156:163], v[50:65], v198, v198 op_sel_hi:[0,0,0]
	v_cvt_pk_fp8_f32 v88, v25, v26
	v_cvt_pk_fp8_f32 v89, v29, v30
	v_cvt_pk_fp8_f32 v85, v80, v81 op_sel:[0,0,1]
	v_cvt_pk_fp8_f32 v86, v20, v21 op_sel:[0,0,1]
	v_cvt_pk_fp8_f32 v87, v23, v24 op_sel:[0,0,1]
	v_cvt_pk_fp8_f32 v88, v27, v28 op_sel:[0,0,1]
	v_cvt_pk_fp8_f32 v89, v31, v32 op_sel:[0,0,1]
	s_waitcnt vmcnt(0) lgkmcnt(0)
	s_barrier
; __device__ __forceinline__ int crow(int r, int hi) { return (r & 3) + 8 * (r >> 2) + 4 * hi; }
; __device__ __forceinline__ unsigned cvtpk_s(float lo, float hi) { f32x2_t v = {lo, hi}; bf16x2_t b = __builtin_convertvector(v, bf16x2_t); return __builtin_bit_cast(unsigned, b); }
; #define FRAG(dst, off) do { const i32x4 lo_ = RD16(fb0, off), hi_ = RD16(fb1, off); dst = (i32x8){lo_[0], lo_[1], lo_[2], lo_[3], hi_[0], hi_[1], hi_[2], hi_[3]}; } while (0)
; #define MFPV(p, v, c) __builtin_amdgcn_mfma_scale_f32_32x32x64_f8f6f4(p, v, c, 0, 0, 0, SC1, 0, SC1)
; __device__ __forceinline__ void attn_unit_f8(const UnitDesc8& U, char* shm) {
;     ...
;     FRAG(vf[0], LDS_V + 3 * TS); FRAG(vf[1], LDS_V + 3 * TS + 2048);
;     o[0] = MFPV(pfB, vf[0], o[0]); o[1] = MFPV(pfB, vf[1], o[1]); ls = MFPV(pfB, ones8, ls);
;     int lane_e = lane; asm volatile("" : "+v"(lane_e));
;     const int r32_e = lane_e & 31, hi_e = lane_e >> 5;
;     asm volatile("s_waitcnt lgkmcnt(0)\n\ts_barrier" ::: "memory");
;     bf16_t* stg = (bf16_t*)shm + wid * 2048;
; #pragma unroll
;     for (int r = 0; r < 16; ++r) { const int orow = crow(r, hi_e); const float rl = __builtin_amdgcn_rcpf(ls[r]);
; #pragma unroll
;         for (int d0 = 0; d0 < 2; ++d0) stg[orow * 64 + d0 * 32 + r32_e] = (bf16_t)(cvtpk_s(o[d0][r] * rl, 0.f) & 0xffffu); }
;     asm volatile("s_waitcnt lgkmcnt(0)" ::: "memory");
; #pragma unroll
;     for (int i = 0; i < 4; ++i) { const int row = i * 8 + (lane_e >> 3), ch = lane_e & 7; const u32x4 v = *(const u32x4*)(stg + row * 64 + ch * 8); *(u32x4*)(U.Ow + (size_t)row * U.OP + ch * 8) = v; }
;     asm volatile("s_waitcnt lgkmcnt(0)\n\ts_barrier" ::: "memory");
	ds_read_b128 v[22:25], v202 offset:28672
	ds_read_b128 v[18:21], v201 offset:28672
	ds_read_b128 v[26:29], v201 offset:30720
	ds_read_b128 v[30:33], v202 offset:30720
	v_mov_b32_e32 v1, v193
	s_lshl_b32 s8, s8, 12
	s_add_i32 s8, s8, 0
	s_waitcnt lgkmcnt(0)
	s_barrier
	v_mfma_scale_f32_32x32x64_f8f6f4 v[34:49], v[124:131], v[148:155], v[34:49], v198, v198 op_sel_hi:[0,0,0]
	v_mfma_scale_f32_32x32x64_f8f6f4 v[2:17], v[140:147], v[116:123], v[2:17], v198, v198 op_sel_hi:[0,0,0]
	v_mfma_scale_f32_32x32x64_f8f6f4 v[50:65], v[140:147], v[172:179], v[50:65], v198, v198 op_sel_hi:[0,0,0]
	v_mfma_scale_f32_32x32x64_f8f6f4 v[34:49], v[140:147], v[164:171], v[34:49], v198, v198 op_sel_hi:[0,0,0]
	v_mfma_scale_f32_32x32x64_f8f6f4 v[2:17], v[98:105], v[116:123], v[2:17], v198, v198 op_sel_hi:[0,0,0]
	s_waitcnt lgkmcnt(4)
	v_mfma_scale_f32_32x32x64_f8f6f4 v[50:65], v[98:105], v[224:231], v[50:65], v198, v198 op_sel_hi:[0,0,0]
	v_mfma_scale_f32_32x32x64_f8f6f4 v[34:49], v[98:105], v[106:113], v[34:49], v198, v198 op_sel_hi:[0,0,0]
	v_mfma_scale_f32_32x32x64_f8f6f4 v[2:17], v[82:89], v[116:123], v[2:17], v198, v198 op_sel_hi:[0,0,0]
	s_waitcnt lgkmcnt(2)
	v_mfma_scale_f32_32x32x64_f8f6f4 v[34:49], v[82:89], v[18:25], v[34:49], v198, v198 op_sel_hi:[0,0,0]
	s_nop 15
	s_nop 1
	v_rcp_f32_e32 v2, v2
	v_and_b32_e32 v18, 31, v1
	v_lshlrev_b32_e32 v19, 4, v1
	v_rcp_f32_e32 v3, v3
	v_lshlrev_b32_e32 v18, 1, v18
	v_and_b32_e32 v20, 0xfffffe00, v19
	v_add3_u32 v18, s8, v18, v20
	v_and_b32_e32 v182, 0x70, v19
	v_mul_f32_e32 v20, v34, v2
	s_waitcnt lgkmcnt(0)
	v_mfma_scale_f32_32x32x64_f8f6f4 v[50:65], v[82:89], v[26:33], v[50:65], v198, v198 op_sel_hi:[0,0,0]
	v_cvt_pk_bf16_f32 v20, v20, s0
	ds_write_b16 v18, v20
	s_nop 15
	s_nop 1
	v_mul_f32_e32 v2, v50, v2
	v_cvt_pk_bf16_f32 v2, v2, s0
	ds_write_b16 v18, v2 offset:64
	v_mul_f32_e32 v2, v35, v3
	v_cvt_pk_bf16_f32 v2, v2, s0
	ds_write_b16 v18, v2 offset:128
	v_rcp_f32_e32 v2, v4
	v_mul_f32_e32 v3, v51, v3
	v_cvt_pk_bf16_f32 v3, v3, s0
	ds_write_b16 v18, v3 offset:192
	v_mul_f32_e32 v3, v36, v2
	v_cvt_pk_bf16_f32 v3, v3, s0
	ds_write_b16 v18, v3 offset:256
	v_rcp_f32_e32 v3, v5
	v_mul_f32_e32 v2, v52, v2
	v_cvt_pk_bf16_f32 v2, v2, s0
	ds_write_b16 v18, v2 offset:320
	v_mul_f32_e32 v2, v37, v3
	v_cvt_pk_bf16_f32 v2, v2, s0
	ds_write_b16 v18, v2 offset:384
	v_rcp_f32_e32 v2, v6
	v_mul_f32_e32 v3, v53, v3
	v_cvt_pk_bf16_f32 v3, v3, s0
	ds_write_b16 v18, v3 offset:448
	v_mul_f32_e32 v3, v38, v2
	v_cvt_pk_bf16_f32 v3, v3, s0
	ds_write_b16 v18, v3 offset:1024
	v_rcp_f32_e32 v3, v7
	v_mul_f32_e32 v2, v54, v2
	v_cvt_pk_bf16_f32 v2, v2, s0
	ds_write_b16 v18, v2 offset:1088
	v_mul_f32_e32 v2, v39, v3
	v_cvt_pk_bf16_f32 v2, v2, s0
	ds_write_b16 v18, v2 offset:1152
	v_rcp_f32_e32 v2, v8
	v_mul_f32_e32 v3, v55, v3
	v_cvt_pk_bf16_f32 v3, v3, s0
	ds_write_b16 v18, v3 offset:1216
	v_mul_f32_e32 v3, v40, v2
	v_cvt_pk_bf16_f32 v3, v3, s0
	ds_write_b16 v18, v3 offset:1280
	v_rcp_f32_e32 v3, v9
	v_mul_f32_e32 v2, v56, v2
	v_cvt_pk_bf16_f32 v2, v2, s0
	ds_write_b16 v18, v2 offset:1344
	v_mul_f32_e32 v2, v41, v3
	v_cvt_pk_bf16_f32 v2, v2, s0
	ds_write_b16 v18, v2 offset:1408
	v_rcp_f32_e32 v2, v10
	v_mul_f32_e32 v3, v57, v3
	v_cvt_pk_bf16_f32 v3, v3, s0
	ds_write_b16 v18, v3 offset:1472
	v_mul_f32_e32 v3, v42, v2
	v_cvt_pk_bf16_f32 v3, v3, s0
	ds_write_b16 v18, v3 offset:2048
	v_rcp_f32_e32 v3, v11
	v_mul_f32_e32 v2, v58, v2
	v_cvt_pk_bf16_f32 v2, v2, s0
	ds_write_b16 v18, v2 offset:2112
	v_mul_f32_e32 v2, v43, v3
	v_cvt_pk_bf16_f32 v2, v2, s0
	ds_write_b16 v18, v2 offset:2176
	v_rcp_f32_e32 v2, v12
	v_mul_f32_e32 v3, v59, v3
	v_cvt_pk_bf16_f32 v3, v3, s0
	ds_write_b16 v18, v3 offset:2240
	v_mul_f32_e32 v3, v44, v2
	v_cvt_pk_bf16_f32 v3, v3, s0
	ds_write_b16 v18, v3 offset:2304
	v_rcp_f32_e32 v3, v13
	v_mul_f32_e32 v2, v60, v2
	v_cvt_pk_bf16_f32 v2, v2, s0
	ds_write_b16 v18, v2 offset:2368
	v_mul_f32_e32 v2, v45, v3
	v_cvt_pk_bf16_f32 v2, v2, s0
	ds_write_b16 v18, v2 offset:2432
	v_rcp_f32_e32 v2, v14
	v_mul_f32_e32 v3, v61, v3
	v_cvt_pk_bf16_f32 v3, v3, s0
	ds_write_b16 v18, v3 offset:2496
	v_mul_f32_e32 v3, v46, v2
	v_cvt_pk_bf16_f32 v3, v3, s0
	ds_write_b16 v18, v3 offset:3072
	v_rcp_f32_e32 v3, v15
	v_mul_f32_e32 v2, v62, v2
	v_cvt_pk_bf16_f32 v2, v2, s0
	ds_write_b16 v18, v2 offset:3136
	v_mul_f32_e32 v2, v47, v3
	v_cvt_pk_bf16_f32 v2, v2, s0
	ds_write_b16 v18, v2 offset:3200
	v_rcp_f32_e32 v2, v16
	v_mul_f32_e32 v3, v63, v3
	v_cvt_pk_bf16_f32 v3, v3, s0
	ds_write_b16 v18, v3 offset:3264
	v_mul_f32_e32 v3, v48, v2
	v_cvt_pk_bf16_f32 v3, v3, s0
	ds_write_b16 v18, v3 offset:3328
	v_rcp_f32_e32 v3, v17
	v_mul_f32_e32 v2, v64, v2
	v_cvt_pk_bf16_f32 v2, v2, s0
	ds_write_b16 v18, v2 offset:3392
	v_mul_f32_e32 v2, v49, v3
	v_cvt_pk_bf16_f32 v2, v2, s0
	ds_write_b16 v18, v2 offset:3456
	v_mul_f32_e32 v2, v65, v3
	v_cvt_pk_bf16_f32 v2, v2, s0
	ds_write_b16 v18, v2 offset:3520
	v_ashrrev_i32_e32 v10, 3, v1
	v_add_u32_e32 v1, s8, v182
	s_waitcnt lgkmcnt(0)
	v_lshl_add_u32 v2, v10, 7, v1
	v_ashrrev_i32_e32 v11, 31, v10
	ds_read_b128 v[2:5], v2
	v_lshlrev_b64 v[6:7], 11, v[10:11]
	v_lshl_add_u64 v[6:7], s[0:1], 0, v[6:7]
	v_add_u32_e32 v14, 8, v10
	v_lshl_add_u64 v[12:13], v[6:7], 0, v[182:183]
	v_lshl_add_u32 v6, v14, 7, v1
	ds_read_b128 v[6:9], v6
	v_ashrrev_i32_e32 v15, 31, v14
	s_waitcnt lgkmcnt(1)
	global_store_dwordx4 v[12:13], v[2:5], off offset:1024 sc0 sc1
	s_nop 1
	v_lshlrev_b64 v[2:3], 11, v[14:15]
	v_lshl_add_u64 v[2:3], s[0:1], 0, v[2:3]
	v_lshl_add_u64 v[2:3], v[2:3], 0, v[182:183]
	s_waitcnt lgkmcnt(0)
	global_store_dwordx4 v[2:3], v[6:9], off offset:1024 sc0 sc1
	s_nop 1
	v_add_u32_e32 v6, 16, v10
	v_lshl_add_u32 v2, v6, 7, v1
	ds_read_b128 v[2:5], v2
	v_ashrrev_i32_e32 v7, 31, v6
	v_lshlrev_b64 v[6:7], 11, v[6:7]
	v_add_u32_e32 v10, 24, v10
	v_lshl_add_u64 v[6:7], s[0:1], 0, v[6:7]
	v_lshl_add_u32 v1, v10, 7, v1
	v_lshl_add_u64 v[12:13], v[6:7], 0, v[182:183]
	ds_read_b128 v[6:9], v1
	v_ashrrev_i32_e32 v11, 31, v10
	s_waitcnt lgkmcnt(1)
	global_store_dwordx4 v[12:13], v[2:5], off offset:1024 sc0 sc1
	s_nop 1
	v_lshlrev_b64 v[2:3], 11, v[10:11]
	v_lshl_add_u64 v[2:3], s[0:1], 0, v[2:3]
	v_lshl_add_u64 v[2:3], v[2:3], 0, v[182:183]
	s_waitcnt lgkmcnt(0)
	global_store_dwordx4 v[2:3], v[6:9], off offset:1024 sc0 sc1
	s_waitcnt lgkmcnt(0)
	s_barrier
	s_branch .LBB0_426

; __device__ __forceinline__ void attn_unit_d16(const UnitDesc& U, char* shm, float lam, const float* subw) {
;     ...
;     if (wid < 4) {
; #pragma unroll
;         for (int qt = 0; qt < 2; ++qt)
; #pragma unroll
;             for (int r = 0; r < 4; ++r) { const float sc = __builtin_amdgcn_rcpf(ls[qt][r]); const int row = 16 * qt + 4 * g_e + r;
; #pragma unroll
;                 for (int dt = 0; dt < 8; ++dt) { const int a = row * 128 + 16 * dt + c16_e; X[a] = o[qt][dt][r] * sc - X[a]; } }
.LBB0_447:
	s_waitcnt lgkmcnt(0)
	s_barrier
	s_cmpk_gt_u32 s12, 0xff
	s_cbranch_scc1 .LBB0_425
	ds_read2_b32 v[22:23], v7 offset1:16
	ds_read2_b32 v[24:25], v7 offset0:32 offset1:48
	ds_read2_b32 v[26:27], v7 offset0:64 offset1:80
	s_lshl_b64 s[0:1], s[0:1], 11
	v_ashrrev_i32_e32 v83, 31, v82
	s_waitcnt lgkmcnt(2)
	v_fma_f32 v22, v70, v21, -v22
	v_fma_f32 v23, v74, v21, -v23
	s_waitcnt lgkmcnt(1)
	v_fma_f32 v24, v58, v21, -v24
	ds_write2_b32 v7, v22, v23 offset1:16
	v_fma_f32 v22, v62, v21, -v25
	ds_write2_b32 v7, v24, v22 offset0:32 offset1:48
	ds_read2_b32 v[22:23], v7 offset0:96 offset1:112
	s_waitcnt lgkmcnt(3)
	v_fma_f32 v24, v66, v21, -v26
	v_fma_f32 v25, v54, v21, -v27
	ds_write2_b32 v7, v24, v25 offset0:64 offset1:80
	ds_read2_b32 v[24:25], v7 offset0:128 offset1:144
	s_waitcnt lgkmcnt(2)
	v_fma_f32 v22, v50, v21, -v22
	v_fma_f32 v21, v78, v21, -v23
	ds_write2_b32 v7, v22, v21 offset0:96 offset1:112
	ds_read2_b32 v[22:23], v7 offset0:160 offset1:176
	s_waitcnt lgkmcnt(2)
	v_fma_f32 v21, v71, v20, -v24
	v_fma_f32 v26, v75, v20, -v25
	ds_read2_b32 v[24:25], v7 offset0:192 offset1:208
	ds_write2_b32 v7, v21, v26 offset0:128 offset1:144
	s_waitcnt lgkmcnt(2)
	v_fma_f32 v21, v59, v20, -v22
	v_fma_f32 v22, v63, v20, -v23
	ds_write2_b32 v7, v21, v22 offset0:160 offset1:176
	ds_read2_b32 v[22:23], v7 offset0:224 offset1:240
	s_waitcnt lgkmcnt(3)
	v_fma_f32 v21, v67, v20, -v24
	v_fma_f32 v24, v55, v20, -v25
	v_add_u32_e32 v26, 0x400, v7
	ds_write2_b32 v7, v21, v24 offset0:192 offset1:208
	ds_read2_b32 v[24:25], v26 offset1:16
	s_waitcnt lgkmcnt(2)
	v_fma_f32 v21, v51, v20, -v22
	v_fma_f32 v20, v79, v20, -v23
	ds_write2_b32 v7, v21, v20 offset0:224 offset1:240
	ds_read2_b32 v[20:21], v26 offset0:32 offset1:48
	s_waitcnt lgkmcnt(2)
	v_fma_f32 v22, v72, v19, -v24
	v_fma_f32 v23, v76, v19, -v25
	ds_write2_b32 v26, v22, v23 offset1:16
	ds_read2_b32 v[22:23], v26 offset0:64 offset1:80
	s_waitcnt lgkmcnt(2)
	v_fma_f32 v20, v60, v19, -v20
	v_fma_f32 v21, v64, v19, -v21
	ds_write2_b32 v26, v20, v21 offset0:32 offset1:48
	ds_read2_b32 v[20:21], v26 offset0:96 offset1:112
	s_waitcnt lgkmcnt(2)
	v_fma_f32 v22, v68, v19, -v22
	v_fma_f32 v23, v56, v19, -v23
	ds_write2_b32 v26, v22, v23 offset0:64 offset1:80
	ds_read2_b32 v[22:23], v26 offset0:128 offset1:144
	s_waitcnt lgkmcnt(2)
	v_fma_f32 v20, v52, v19, -v20
	v_fma_f32 v19, v80, v19, -v21
	ds_write2_b32 v26, v20, v19 offset0:96 offset1:112
	ds_read2_b32 v[20:21], v26 offset0:160 offset1:176
	s_waitcnt lgkmcnt(2)
	v_fma_f32 v19, v73, v18, -v22
	v_fma_f32 v24, v77, v18, -v23
	ds_read2_b32 v[22:23], v26 offset0:192 offset1:208
	ds_write2_b32 v26, v19, v24 offset0:128 offset1:144
	s_waitcnt lgkmcnt(2)
	v_fma_f32 v19, v61, v18, -v20
	v_fma_f32 v20, v65, v18, -v21
	ds_write2_b32 v26, v19, v20 offset0:160 offset1:176
	ds_read2_b32 v[20:21], v26 offset0:224 offset1:240
	s_waitcnt lgkmcnt(3)
	v_fma_f32 v19, v69, v18, -v22
	v_fma_f32 v22, v57, v18, -v23
	v_add_u32_e32 v24, 0x2000, v7
	ds_write2_b32 v26, v19, v22 offset0:192 offset1:208
	ds_read2_b32 v[22:23], v24 offset1:16
	s_waitcnt lgkmcnt(2)
	v_fma_f32 v19, v53, v18, -v20
	v_fma_f32 v18, v81, v18, -v21
	ds_write2_b32 v26, v19, v18 offset0:224 offset1:240
	ds_read2_b32 v[18:19], v24 offset0:32 offset1:48
	s_waitcnt lgkmcnt(2)
	v_fma_f32 v20, v38, v9, -v22
	v_fma_f32 v21, v42, v9, -v23
	ds_write2_b32 v24, v20, v21 offset1:16
	ds_read2_b32 v[20:21], v24 offset0:64 offset1:80
	s_waitcnt lgkmcnt(2)
	v_fma_f32 v18, v30, v9, -v18
	v_fma_f32 v19, v34, v9, -v19
	ds_write2_b32 v24, v18, v19 offset0:32 offset1:48
	ds_read2_b32 v[18:19], v24 offset0:96 offset1:112
	s_waitcnt lgkmcnt(2)
	v_fma_f32 v10, v10, v9, -v20
	v_fma_f32 v14, v14, v9, -v21
	ds_read2_b32 v[20:21], v24 offset0:128 offset1:144
	ds_write2_b32 v24, v10, v14 offset0:64 offset1:80
	s_waitcnt lgkmcnt(2)
	v_fma_f32 v10, v46, v9, -v18
	v_fma_f32 v2, v2, v9, -v19
	ds_read2_b32 v[18:19], v24 offset0:160 offset1:176
	ds_write2_b32 v24, v10, v2 offset0:96 offset1:112
	s_waitcnt lgkmcnt(3)
	v_fma_f32 v2, v39, v8, -v20
	v_fma_f32 v9, v43, v8, -v21
	ds_read2_b32 v[20:21], v24 offset0:192 offset1:208
	ds_write2_b32 v24, v2, v9 offset0:128 offset1:144
	s_waitcnt lgkmcnt(3)
	v_fma_f32 v2, v31, v8, -v18
	v_fma_f32 v9, v35, v8, -v19
	ds_write2_b32 v24, v2, v9 offset0:160 offset1:176
	s_waitcnt lgkmcnt(2)
	v_fma_f32 v2, v11, v8, -v20
	ds_read2_b32 v[10:11], v24 offset0:224 offset1:240
	v_fma_f32 v9, v15, v8, -v21
	v_add_u32_e32 v18, 0x2400, v7
	ds_write2_b32 v24, v2, v9 offset0:192 offset1:208
	ds_read2_b32 v[14:15], v18 offset1:16
	s_waitcnt lgkmcnt(2)
	v_fma_f32 v2, v47, v8, -v10
	v_fma_f32 v3, v3, v8, -v11
	ds_write2_b32 v24, v2, v3 offset0:224 offset1:240
	ds_read2_b32 v[2:3], v18 offset0:32 offset1:48
	s_waitcnt lgkmcnt(2)
	v_fma_f32 v7, v40, v6, -v14
	v_fma_f32 v8, v44, v6, -v15
	ds_write2_b32 v18, v7, v8 offset1:16
	ds_read2_b32 v[8:9], v18 offset0:64 offset1:80
	s_waitcnt lgkmcnt(2)
	v_fma_f32 v2, v32, v6, -v2
	v_fma_f32 v3, v36, v6, -v3
	ds_write2_b32 v18, v2, v3 offset0:32 offset1:48
	ds_read2_b32 v[2:3], v18 offset0:96 offset1:112
	s_waitcnt lgkmcnt(2)
	v_fma_f32 v7, v12, v6, -v8
	v_fma_f32 v8, v16, v6, -v9
	ds_write2_b32 v18, v7, v8 offset0:64 offset1:80
	ds_read2_b32 v[8:9], v18 offset0:128 offset1:144
	s_waitcnt lgkmcnt(2)
	v_fma_f32 v2, v48, v6, -v2
	v_fma_f32 v3, v4, v6, -v3
	ds_write2_b32 v18, v2, v3 offset0:96 offset1:112
	ds_read2_b32 v[2:3], v18 offset0:160 offset1:176
	s_waitcnt lgkmcnt(2)
	v_fma_f32 v4, v41, v1, -v8
	v_fma_f32 v6, v45, v1, -v9
	ds_write2_b32 v18, v4, v6 offset0:128 offset1:144
	ds_read2_b32 v[6:7], v18 offset0:192 offset1:208
	s_waitcnt lgkmcnt(2)
; __device__ __forceinline__ unsigned cvtpk_s(float lo, float hi) { f32x2_t v = {lo, hi}; bf16x2_t b = __builtin_convertvector(v, bf16x2_t); return __builtin_bit_cast(unsigned, b); }
; __device__ __forceinline__ void attn_unit_d16(const UnitDesc& U, char* shm, float lam, const float* subw) {
;     ...
;         asm volatile("s_waitcnt lgkmcnt(0)" ::: "memory");
;         const int ch = lane_e & 15;
;         const f32x4 w0 = *(const f32x4*)(subw + ch * 8), w1 = *(const f32x4*)(subw + ch * 8 + 4);
; #pragma unroll
;         for (int i = 0; i < 8; ++i) { const int row = i * 4 + (lane_e >> 4);
;             const f32x4 v0 = *(const f32x4*)(X + row * 128 + ch * 8), v1 = *(const f32x4*)(X + row * 128 + ch * 8 + 4);
;             float ss = v0[0] * v0[0] + v0[1] * v0[1] + v0[2] * v0[2] + v0[3] * v0[3] + v1[0] * v1[0] + v1[1] * v1[1] + v1[2] * v1[2] + v1[3] * v1[3];
;             ss += __shfl_xor(ss, 1); ss += __shfl_xor(ss, 2); ss += __shfl_xor(ss, 4); ss += __shfl_xor(ss, 8);
;             const float rs = (1.0f - LAMBDA_INIT) / sqrtf(ss * (1.0f / 128.0f) + EPS);
;             u32x4 w; w.x = cvtpk_s(v0[0] * rs * w0[0], v0[1] * rs * w0[1]); w.y = cvtpk_s(v0[2] * rs * w0[2], v0[3] * rs * w0[3]);
;             w.z = cvtpk_s(v1[0] * rs * w1[0], v1[1] * rs * w1[1]); w.w = cvtpk_s(v1[2] * rs * w1[2], v1[3] * rs * w1[3]);
;             *(u32x4*)(U.Ow + (size_t)row * D + ch * 8) = w; }
	v_fma_f32 v4, v33, v1, -v2
	v_fma_f32 v8, v37, v1, -v3
	ds_read2_b32 v[2:3], v18 offset0:224 offset1:240
	ds_write2_b32 v18, v4, v8 offset0:160 offset1:176
	s_waitcnt lgkmcnt(2)
	v_fma_f32 v4, v13, v1, -v6
	v_fma_f32 v6, v17, v1, -v7
	ds_write2_b32 v18, v4, v6 offset0:192 offset1:208
	s_waitcnt lgkmcnt(2)
	v_fma_f32 v2, v49, v1, -v2
	v_fma_f32 v1, v5, v1, -v3
	ds_write2_b32 v18, v2, v1 offset0:224 offset1:240
	s_waitcnt lgkmcnt(0)
	v_lshlrev_b32_e32 v1, 5, v84
	global_load_dwordx4 v[2:5], v1, s[36:37] offset:16
	global_load_dwordx4 v[6:9], v1, s[36:37]
	v_add_u32_e32 v1, s10, v1
	v_and_b32_e32 v11, 64, v207
	v_add_u32_e32 v24, 64, v11
	v_lshl_add_u32 v11, v82, 9, v1
	ds_read_b128 v[14:17], v11
	ds_read_b128 v[18:21], v11 offset:16
	v_xor_b32_e32 v10, 1, v207
	v_cmp_lt_i32_e32 vcc, v10, v24
	s_add_u32 s10, s94, s0
	s_waitcnt lgkmcnt(1)
	v_mul_f32_e32 v11, v15, v15
	v_fmac_f32_e32 v11, v14, v14
	v_fmac_f32_e32 v11, v16, v16
	v_fmac_f32_e32 v11, v17, v17
	s_waitcnt lgkmcnt(0)
	v_pk_mul_f32 v[22:23], v[18:19], v[18:19]
	v_pk_mul_f32 v[12:13], v[20:21], v[20:21]
	v_add_f32_e32 v11, v22, v11
	v_add_f32_e32 v11, v23, v11
	v_cndmask_b32_e32 v10, v207, v10, vcc
	v_add_f32_e32 v11, v12, v11
	v_lshlrev_b32_e32 v10, 2, v10
	v_add_f32_e32 v12, v13, v11
	ds_bpermute_b32 v13, v10, v12
	v_xor_b32_e32 v11, 2, v207
	v_cmp_lt_i32_e32 vcc, v11, v24
	s_addc_u32 s11, s95, s1
	v_add_u32_e32 v30, 4, v82
	v_cndmask_b32_e32 v11, v207, v11, vcc
	v_lshlrev_b32_e32 v11, 2, v11
	s_waitcnt lgkmcnt(0)
	v_add_f32_e32 v13, v12, v13
	ds_bpermute_b32 v22, v11, v13
	v_xor_b32_e32 v12, 4, v207
	v_cmp_lt_i32_e32 vcc, v12, v24
	v_lshl_add_u32 v26, v30, 9, v1
	v_lshlrev_b32_e32 v182, 4, v84
	v_cndmask_b32_e32 v12, v207, v12, vcc
	v_lshlrev_b32_e32 v12, 2, v12
	s_waitcnt lgkmcnt(0)
	v_add_f32_e32 v22, v13, v22
	ds_bpermute_b32 v23, v12, v22
	v_xor_b32_e32 v13, 8, v207
	v_cmp_lt_i32_e32 vcc, v13, v24
	s_waitcnt lgkmcnt(0)
	v_add_f32_e32 v22, v22, v23
	v_cndmask_b32_e32 v13, v207, v13, vcc
	v_lshlrev_b32_e32 v13, 2, v13
	ds_bpermute_b32 v23, v13, v22
	s_waitcnt lgkmcnt(0)
	v_add_f32_e32 v22, v22, v23
	v_fmamk_f32 v22, v22, 0x3c000000, v199
	v_mul_f32_e32 v23, 0x4f800000, v22
	v_cmp_gt_f32_e32 vcc, s49, v22
	s_nop 1
	v_cndmask_b32_e32 v22, v22, v23, vcc
	v_sqrt_f32_e32 v23, v22
	s_nop 0
	v_add_u32_e32 v24, -1, v23
	v_fma_f32 v25, -v24, v23, v22
	v_cmp_ge_f32_e64 s[0:1], 0, v25
	v_add_u32_e32 v25, 1, v23
	s_nop 0
	v_cndmask_b32_e64 v24, v23, v24, s[0:1]
	v_fma_f32 v23, -v25, v23, v22
	v_cmp_lt_f32_e64 s[0:1], 0, v23
	s_nop 1
	v_cndmask_b32_e64 v23, v24, v25, s[0:1]
	v_mul_f32_e32 v24, 0x37800000, v23
	v_cndmask_b32_e32 v23, v23, v24, vcc
	v_cmp_class_f32_e32 vcc, v22, v200
	s_nop 1
	v_cndmask_b32_e32 v31, v23, v22, vcc
	v_div_scale_f32 v36, s[0:1], v31, v31, s50
	v_rcp_f32_e32 v37, v36
	v_div_scale_f32 v38, vcc, s50, v31, s50
	s_lshl_b32 s0, s8, 1
	v_fma_f32 v22, -v36, v37, 1.0
	v_fmac_f32_e32 v37, v22, v37
	ds_read_b128 v[22:25], v26
	v_mul_f32_e32 v39, v38, v37
	v_fma_f32 v27, -v36, v39, v38
	v_fmac_f32_e32 v39, v27, v37
	ds_read_b128 v[26:29], v26 offset:16
	s_waitcnt lgkmcnt(1)
	v_mul_f32_e32 v40, v23, v23
	v_fmac_f32_e32 v40, v22, v22
	v_fmac_f32_e32 v40, v24, v24
	v_fmac_f32_e32 v40, v25, v25
	s_waitcnt lgkmcnt(0)
	v_pk_mul_f32 v[34:35], v[26:27], v[26:27]
	v_pk_mul_f32 v[32:33], v[28:29], v[28:29]
	v_add_f32_e32 v34, v34, v40
	v_add_f32_e32 v34, v35, v34
	v_add_f32_e32 v32, v32, v34
	v_add_f32_e32 v33, v33, v32
	ds_bpermute_b32 v34, v10, v33
	v_fma_f32 v32, -v36, v39, v38
	v_div_fmas_f32 v32, v32, v37, v39
	v_div_fixup_f32 v32, v32, v31, s50
	s_add_u32 s10, s10, s0
	s_waitcnt lgkmcnt(0)
	v_add_f32_e32 v31, v33, v34
	ds_bpermute_b32 v33, v11, v31
	s_addc_u32 s11, s11, 0
	s_waitcnt lgkmcnt(0)
	v_add_f32_e32 v31, v31, v33
	v_pk_mul_f32 v[14:15], v[14:15], v[32:33] op_sel_hi:[1,0]
	v_pk_mul_f32 v[16:17], v[16:17], v[32:33] op_sel_hi:[1,0]
	ds_bpermute_b32 v33, v12, v31
	s_waitcnt vmcnt(0)
	v_pk_mul_f32 v[14:15], v[6:7], v[14:15]
	v_pk_mul_f32 v[16:17], v[8:9], v[16:17]
	v_cvt_pk_bf16_f32 v14, v14, v15
	v_cvt_pk_bf16_f32 v15, v16, v17
	s_waitcnt lgkmcnt(0)
	v_add_f32_e32 v31, v31, v33
	v_pk_mul_f32 v[16:17], v[18:19], v[32:33] op_sel_hi:[1,0]
	ds_bpermute_b32 v33, v13, v31
	v_pk_mul_f32 v[16:17], v[2:3], v[16:17]
	s_waitcnt lgkmcnt(0)
	v_pk_mul_f32 v[18:19], v[20:21], v[32:33] op_sel_hi:[1,0]
	s_nop 0
	v_pk_mul_f32 v[18:19], v[4:5], v[18:19]
	v_cvt_pk_bf16_f32 v16, v16, v17
	v_cvt_pk_bf16_f32 v17, v18, v19
	v_add_f32_e32 v18, v31, v33
	v_fmamk_f32 v18, v18, 0x3c000000, v199
	v_mul_f32_e32 v19, 0x4f800000, v18
	v_cmp_gt_f32_e32 vcc, s49, v18
	s_nop 1
	v_cndmask_b32_e32 v20, v18, v19, vcc
	v_sqrt_f32_e32 v21, v20
	v_lshlrev_b64 v[18:19], 11, v[82:83]
	v_lshl_add_u64 v[18:19], s[10:11], 0, v[18:19]
	v_lshl_add_u64 v[18:19], v[18:19], 0, v[182:183]
	v_add_u32_e32 v31, -1, v21
	v_fma_f32 v32, -v31, v21, v20
	v_cmp_ge_f32_e64 s[0:1], 0, v32
	v_add_u32_e32 v32, 1, v21
	global_store_dwordx4 v[18:19], v[14:17], off sc0 sc1
	v_cndmask_b32_e64 v31, v21, v31, s[0:1]
	v_fma_f32 v21, -v32, v21, v20
	v_cmp_lt_f32_e64 s[0:1], 0, v21
	s_nop 1
	v_cndmask_b32_e64 v21, v31, v32, s[0:1]
	v_mul_f32_e32 v31, 0x37800000, v21
	v_cndmask_b32_e32 v21, v21, v31, vcc
	v_cmp_class_f32_e32 vcc, v20, v200
	v_add_u32_e32 v32, 8, v82
	v_lshl_add_u32 v18, v32, 9, v1
	v_cndmask_b32_e32 v31, v21, v20, vcc
	v_div_scale_f32 v33, s[0:1], v31, v31, s50
	v_rcp_f32_e32 v38, v33
	v_div_scale_f32 v39, vcc, s50, v31, s50
	v_fma_f32 v14, -v33, v38, 1.0
	v_fmac_f32_e32 v38, v14, v38
	ds_read_b128 v[14:17], v18
	ds_read_b128 v[18:21], v18 offset:16
	v_mul_f32_e32 v40, v39, v38
	v_fma_f32 v41, -v33, v40, v39
	v_fmac_f32_e32 v40, v41, v38
	s_waitcnt lgkmcnt(1)
; __device__ __forceinline__ unsigned cvtpk_s(float lo, float hi) { f32x2_t v = {lo, hi}; bf16x2_t b = __builtin_convertvector(v, bf16x2_t); return __builtin_bit_cast(unsigned, b); }
; __device__ __forceinline__ void attn_unit_d16(const UnitDesc& U, char* shm, float lam, const float* subw) {
;     ...
;         for (int i = 0; i < 8; ++i) { const int row = i * 4 + (lane_e >> 4);
;             const f32x4 v0 = *(const f32x4*)(X + row * 128 + ch * 8), v1 = *(const f32x4*)(X + row * 128 + ch * 8 + 4);
;             float ss = v0[0] * v0[0] + v0[1] * v0[1] + v0[2] * v0[2] + v0[3] * v0[3] + v1[0] * v1[0] + v1[1] * v1[1] + v1[2] * v1[2] + v1[3] * v1[3];
;             ss += __shfl_xor(ss, 1); ss += __shfl_xor(ss, 2); ss += __shfl_xor(ss, 4); ss += __shfl_xor(ss, 8);
;             const float rs = (1.0f - LAMBDA_INIT) / sqrtf(ss * (1.0f / 128.0f) + EPS);
;             u32x4 w; w.x = cvtpk_s(v0[0] * rs * w0[0], v0[1] * rs * w0[1]); w.y = cvtpk_s(v0[2] * rs * w0[2], v0[3] * rs * w0[3]);
;             w.z = cvtpk_s(v1[0] * rs * w1[0], v1[1] * rs * w1[1]); w.w = cvtpk_s(v1[2] * rs * w1[2], v1[3] * rs * w1[3]);
;             *(u32x4*)(U.Ow + (size_t)row * D + ch * 8) = w; }
	v_mul_f32_e32 v42, v15, v15
	v_fmac_f32_e32 v42, v14, v14
	v_fmac_f32_e32 v42, v16, v16
	v_fmac_f32_e32 v42, v17, v17
	s_waitcnt lgkmcnt(0)
	v_pk_mul_f32 v[36:37], v[18:19], v[18:19]
	v_pk_mul_f32 v[34:35], v[20:21], v[20:21]
	v_add_f32_e32 v36, v36, v42
	v_add_f32_e32 v36, v37, v36
	v_add_f32_e32 v34, v34, v36
	v_add_f32_e32 v34, v35, v34
	ds_bpermute_b32 v35, v10, v34
	v_fma_f32 v33, -v33, v40, v39
	v_div_fmas_f32 v33, v33, v38, v40
	s_waitcnt lgkmcnt(0)
	v_add_f32_e32 v35, v34, v35
	ds_bpermute_b32 v36, v11, v35
	v_div_fixup_f32 v34, v33, v31, s50
	v_pk_mul_f32 v[22:23], v[22:23], v[34:35] op_sel_hi:[1,0]
	v_pk_mul_f32 v[24:25], v[24:25], v[34:35] op_sel_hi:[1,0]
	v_pk_mul_f32 v[22:23], v[6:7], v[22:23]
	s_waitcnt lgkmcnt(0)
	v_add_f32_e32 v31, v35, v36
	ds_bpermute_b32 v33, v12, v31
	v_pk_mul_f32 v[24:25], v[8:9], v[24:25]
	v_cvt_pk_bf16_f32 v22, v22, v23
	v_cvt_pk_bf16_f32 v23, v24, v25
	v_pk_mul_f32 v[24:25], v[26:27], v[34:35] op_sel_hi:[1,0]
	s_waitcnt lgkmcnt(0)
	v_add_f32_e32 v31, v31, v33
	ds_bpermute_b32 v33, v13, v31
	v_pk_mul_f32 v[24:25], v[2:3], v[24:25]
	v_pk_mul_f32 v[26:27], v[28:29], v[34:35] op_sel_hi:[1,0]
	v_cvt_pk_bf16_f32 v24, v24, v25
	v_pk_mul_f32 v[26:27], v[4:5], v[26:27]
	s_waitcnt lgkmcnt(0)
	v_add_f32_e32 v25, v31, v33
	v_fmamk_f32 v25, v25, 0x3c000000, v199
	v_mul_f32_e32 v28, 0x4f800000, v25
	v_cmp_gt_f32_e32 vcc, s49, v25
	v_ashrrev_i32_e32 v31, 31, v30
	s_nop 0
	v_cndmask_b32_e32 v28, v25, v28, vcc
	v_sqrt_f32_e32 v29, v28
	v_cvt_pk_bf16_f32 v25, v26, v27
	v_lshlrev_b64 v[26:27], 11, v[30:31]
	v_lshl_add_u64 v[26:27], s[10:11], 0, v[26:27]
	v_add_u32_e32 v30, -1, v29
	v_fma_f32 v31, -v30, v29, v28
	v_cmp_ge_f32_e64 s[0:1], 0, v31
	v_add_u32_e32 v31, 1, v29
	v_lshl_add_u64 v[26:27], v[26:27], 0, v[182:183]
	v_cndmask_b32_e64 v30, v29, v30, s[0:1]
	v_fma_f32 v29, -v31, v29, v28
	v_cmp_lt_f32_e64 s[0:1], 0, v29
	global_store_dwordx4 v[26:27], v[22:25], off sc0 sc1
	s_nop 0
	v_cndmask_b32_e64 v29, v30, v31, s[0:1]
	v_mul_f32_e32 v30, 0x37800000, v29
	v_cndmask_b32_e32 v29, v29, v30, vcc
	v_cmp_class_f32_e32 vcc, v28, v200
	v_add_u32_e32 v30, 12, v82
	v_lshl_add_u32 v26, v30, 9, v1
	v_cndmask_b32_e32 v31, v29, v28, vcc
	v_div_scale_f32 v33, s[0:1], v31, v31, s50
	v_rcp_f32_e32 v38, v33
	v_div_scale_f32 v39, vcc, s50, v31, s50
	v_fma_f32 v22, -v33, v38, 1.0
	v_fmac_f32_e32 v38, v22, v38
	ds_read_b128 v[22:25], v26
	ds_read_b128 v[26:29], v26 offset:16
	v_mul_f32_e32 v40, v39, v38
	v_fma_f32 v41, -v33, v40, v39
	v_fmac_f32_e32 v40, v41, v38
	s_waitcnt lgkmcnt(1)
	v_mul_f32_e32 v42, v23, v23
	v_fmac_f32_e32 v42, v22, v22
	v_fmac_f32_e32 v42, v24, v24
	v_fmac_f32_e32 v42, v25, v25
	s_waitcnt lgkmcnt(0)
	v_pk_mul_f32 v[36:37], v[26:27], v[26:27]
	v_pk_mul_f32 v[34:35], v[28:29], v[28:29]
	v_add_f32_e32 v36, v36, v42
	v_add_f32_e32 v36, v37, v36
	v_add_f32_e32 v34, v34, v36
	v_add_f32_e32 v34, v35, v34
	ds_bpermute_b32 v35, v10, v34
	v_fma_f32 v33, -v33, v40, v39
	v_div_fmas_f32 v33, v33, v38, v40
	s_waitcnt lgkmcnt(0)
	v_add_f32_e32 v35, v34, v35
	ds_bpermute_b32 v36, v11, v35
	v_div_fixup_f32 v34, v33, v31, s50
	v_pk_mul_f32 v[14:15], v[14:15], v[34:35] op_sel_hi:[1,0]
	v_pk_mul_f32 v[16:17], v[16:17], v[34:35] op_sel_hi:[1,0]
	v_pk_mul_f32 v[14:15], v[6:7], v[14:15]
	s_waitcnt lgkmcnt(0)
	v_add_f32_e32 v31, v35, v36
	ds_bpermute_b32 v33, v12, v31
	v_pk_mul_f32 v[16:17], v[8:9], v[16:17]
	v_cvt_pk_bf16_f32 v14, v14, v15
	v_cvt_pk_bf16_f32 v15, v16, v17
	v_pk_mul_f32 v[16:17], v[18:19], v[34:35] op_sel_hi:[1,0]
	s_waitcnt lgkmcnt(0)
	v_add_f32_e32 v31, v31, v33
	ds_bpermute_b32 v33, v13, v31
	v_pk_mul_f32 v[16:17], v[2:3], v[16:17]
	v_pk_mul_f32 v[18:19], v[20:21], v[34:35] op_sel_hi:[1,0]
	v_cvt_pk_bf16_f32 v16, v16, v17
	v_pk_mul_f32 v[18:19], v[4:5], v[18:19]
	s_waitcnt lgkmcnt(0)
	v_add_f32_e32 v17, v31, v33
	v_fmamk_f32 v17, v17, 0x3c000000, v199
	v_mul_f32_e32 v20, 0x4f800000, v17
	v_cmp_gt_f32_e32 vcc, s49, v17
	v_ashrrev_i32_e32 v33, 31, v32
	s_nop 0
	v_cndmask_b32_e32 v20, v17, v20, vcc
	v_sqrt_f32_e32 v21, v20
	v_cvt_pk_bf16_f32 v17, v18, v19
	v_lshlrev_b64 v[18:19], 11, v[32:33]
	v_lshl_add_u64 v[18:19], s[10:11], 0, v[18:19]
	v_add_u32_e32 v31, -1, v21
	v_fma_f32 v32, -v31, v21, v20
	v_cmp_ge_f32_e64 s[0:1], 0, v32
	v_add_u32_e32 v32, 1, v21
	v_lshl_add_u64 v[18:19], v[18:19], 0, v[182:183]
	v_cndmask_b32_e64 v31, v21, v31, s[0:1]
	v_fma_f32 v21, -v32, v21, v20
	v_cmp_lt_f32_e64 s[0:1], 0, v21
	global_store_dwordx4 v[18:19], v[14:17], off sc0 sc1
	s_nop 0
	v_cndmask_b32_e64 v21, v31, v32, s[0:1]
	v_mul_f32_e32 v31, 0x37800000, v21
	v_cndmask_b32_e32 v21, v21, v31, vcc
	v_cmp_class_f32_e32 vcc, v20, v200
	v_add_u32_e32 v32, 16, v82
	v_lshl_add_u32 v18, v32, 9, v1
	v_cndmask_b32_e32 v31, v21, v20, vcc
	v_div_scale_f32 v33, s[0:1], v31, v31, s50
	v_rcp_f32_e32 v38, v33
	v_div_scale_f32 v39, vcc, s50, v31, s50
	v_fma_f32 v14, -v33, v38, 1.0
	v_fmac_f32_e32 v38, v14, v38
	ds_read_b128 v[14:17], v18
	ds_read_b128 v[18:21], v18 offset:16
	v_mul_f32_e32 v40, v39, v38
	v_fma_f32 v41, -v33, v40, v39
	v_fmac_f32_e32 v40, v41, v38
	s_waitcnt lgkmcnt(1)
	v_mul_f32_e32 v42, v15, v15
	v_fmac_f32_e32 v42, v14, v14
	v_fmac_f32_e32 v42, v16, v16
	v_fmac_f32_e32 v42, v17, v17
	s_waitcnt lgkmcnt(0)
	v_pk_mul_f32 v[36:37], v[18:19], v[18:19]
	v_pk_mul_f32 v[34:35], v[20:21], v[20:21]
	v_add_f32_e32 v36, v36, v42
	v_add_f32_e32 v36, v37, v36
	v_add_f32_e32 v34, v34, v36
	v_add_f32_e32 v34, v35, v34
	ds_bpermute_b32 v35, v10, v34
	v_fma_f32 v33, -v33, v40, v39
	v_div_fmas_f32 v33, v33, v38, v40
	s_waitcnt lgkmcnt(0)
; __device__ __forceinline__ unsigned cvtpk_s(float lo, float hi) { f32x2_t v = {lo, hi}; bf16x2_t b = __builtin_convertvector(v, bf16x2_t); return __builtin_bit_cast(unsigned, b); }
; __device__ __forceinline__ void attn_unit_d16(const UnitDesc& U, char* shm, float lam, const float* subw) {
;     ...
;         for (int i = 0; i < 8; ++i) { const int row = i * 4 + (lane_e >> 4);
;             const f32x4 v0 = *(const f32x4*)(X + row * 128 + ch * 8), v1 = *(const f32x4*)(X + row * 128 + ch * 8 + 4);
;             float ss = v0[0] * v0[0] + v0[1] * v0[1] + v0[2] * v0[2] + v0[3] * v0[3] + v1[0] * v1[0] + v1[1] * v1[1] + v1[2] * v1[2] + v1[3] * v1[3];
;             ss += __shfl_xor(ss, 1); ss += __shfl_xor(ss, 2); ss += __shfl_xor(ss, 4); ss += __shfl_xor(ss, 8);
;             const float rs = (1.0f - LAMBDA_INIT) / sqrtf(ss * (1.0f / 128.0f) + EPS);
;             u32x4 w; w.x = cvtpk_s(v0[0] * rs * w0[0], v0[1] * rs * w0[1]); w.y = cvtpk_s(v0[2] * rs * w0[2], v0[3] * rs * w0[3]);
;             w.z = cvtpk_s(v1[0] * rs * w1[0], v1[1] * rs * w1[1]); w.w = cvtpk_s(v1[2] * rs * w1[2], v1[3] * rs * w1[3]);
;             *(u32x4*)(U.Ow + (size_t)row * D + ch * 8) = w; }
	v_add_f32_e32 v35, v34, v35
	ds_bpermute_b32 v36, v11, v35
	v_div_fixup_f32 v34, v33, v31, s50
	v_pk_mul_f32 v[22:23], v[22:23], v[34:35] op_sel_hi:[1,0]
	v_pk_mul_f32 v[24:25], v[24:25], v[34:35] op_sel_hi:[1,0]
	v_pk_mul_f32 v[22:23], v[6:7], v[22:23]
	s_waitcnt lgkmcnt(0)
	v_add_f32_e32 v31, v35, v36
	ds_bpermute_b32 v33, v12, v31
	v_pk_mul_f32 v[24:25], v[8:9], v[24:25]
	v_cvt_pk_bf16_f32 v22, v22, v23
	v_cvt_pk_bf16_f32 v23, v24, v25
	v_pk_mul_f32 v[24:25], v[26:27], v[34:35] op_sel_hi:[1,0]
	s_waitcnt lgkmcnt(0)
	v_add_f32_e32 v31, v31, v33
	ds_bpermute_b32 v33, v13, v31
	v_pk_mul_f32 v[24:25], v[2:3], v[24:25]
	v_pk_mul_f32 v[26:27], v[28:29], v[34:35] op_sel_hi:[1,0]
	v_cvt_pk_bf16_f32 v24, v24, v25
	v_pk_mul_f32 v[26:27], v[4:5], v[26:27]
	s_waitcnt lgkmcnt(0)
	v_add_f32_e32 v25, v31, v33
	v_fmamk_f32 v25, v25, 0x3c000000, v199
	v_mul_f32_e32 v28, 0x4f800000, v25
	v_cmp_gt_f32_e32 vcc, s49, v25
	v_ashrrev_i32_e32 v31, 31, v30
	s_nop 0
	v_cndmask_b32_e32 v28, v25, v28, vcc
	v_sqrt_f32_e32 v29, v28
	v_cvt_pk_bf16_f32 v25, v26, v27
	v_lshlrev_b64 v[26:27], 11, v[30:31]
	v_lshl_add_u64 v[26:27], s[10:11], 0, v[26:27]
	v_add_u32_e32 v30, -1, v29
	v_fma_f32 v31, -v30, v29, v28
	v_cmp_ge_f32_e64 s[0:1], 0, v31
	v_add_u32_e32 v31, 1, v29
	v_lshl_add_u64 v[26:27], v[26:27], 0, v[182:183]
	v_cndmask_b32_e64 v30, v29, v30, s[0:1]
	v_fma_f32 v29, -v31, v29, v28
	v_cmp_lt_f32_e64 s[0:1], 0, v29
	global_store_dwordx4 v[26:27], v[22:25], off sc0 sc1
	s_nop 0
	v_cndmask_b32_e64 v29, v30, v31, s[0:1]
	v_mul_f32_e32 v30, 0x37800000, v29
	v_cndmask_b32_e32 v29, v29, v30, vcc
	v_cmp_class_f32_e32 vcc, v28, v200
	v_add_u32_e32 v30, 20, v82
	v_lshl_add_u32 v26, v30, 9, v1
	v_cndmask_b32_e32 v31, v29, v28, vcc
	v_div_scale_f32 v33, s[0:1], v31, v31, s50
	v_rcp_f32_e32 v38, v33
	v_div_scale_f32 v39, vcc, s50, v31, s50
	v_fma_f32 v22, -v33, v38, 1.0
	v_fmac_f32_e32 v38, v22, v38
	ds_read_b128 v[22:25], v26
	ds_read_b128 v[26:29], v26 offset:16
	v_mul_f32_e32 v40, v39, v38
	v_fma_f32 v41, -v33, v40, v39
	v_fmac_f32_e32 v40, v41, v38
	s_waitcnt lgkmcnt(1)
	v_mul_f32_e32 v42, v23, v23
	v_fmac_f32_e32 v42, v22, v22
	v_fmac_f32_e32 v42, v24, v24
	v_fmac_f32_e32 v42, v25, v25
	s_waitcnt lgkmcnt(0)
	v_pk_mul_f32 v[36:37], v[26:27], v[26:27]
	v_pk_mul_f32 v[34:35], v[28:29], v[28:29]
	v_add_f32_e32 v36, v36, v42
	v_add_f32_e32 v36, v37, v36
	v_add_f32_e32 v34, v34, v36
	v_add_f32_e32 v34, v35, v34
	ds_bpermute_b32 v35, v10, v34
	v_fma_f32 v33, -v33, v40, v39
	v_div_fmas_f32 v33, v33, v38, v40
	s_waitcnt lgkmcnt(0)
	v_add_f32_e32 v35, v34, v35
	ds_bpermute_b32 v36, v11, v35
	v_div_fixup_f32 v34, v33, v31, s50
	v_pk_mul_f32 v[14:15], v[14:15], v[34:35] op_sel_hi:[1,0]
	v_pk_mul_f32 v[16:17], v[16:17], v[34:35] op_sel_hi:[1,0]
	v_pk_mul_f32 v[14:15], v[6:7], v[14:15]
	s_waitcnt lgkmcnt(0)
	v_add_f32_e32 v31, v35, v36
	ds_bpermute_b32 v33, v12, v31
	v_pk_mul_f32 v[16:17], v[8:9], v[16:17]
	v_cvt_pk_bf16_f32 v14, v14, v15
	v_cvt_pk_bf16_f32 v15, v16, v17
	v_pk_mul_f32 v[16:17], v[18:19], v[34:35] op_sel_hi:[1,0]
	s_waitcnt lgkmcnt(0)
	v_add_f32_e32 v31, v31, v33
	ds_bpermute_b32 v33, v13, v31
	v_pk_mul_f32 v[16:17], v[2:3], v[16:17]
	v_pk_mul_f32 v[18:19], v[20:21], v[34:35] op_sel_hi:[1,0]
	v_cvt_pk_bf16_f32 v16, v16, v17
	v_pk_mul_f32 v[18:19], v[4:5], v[18:19]
	s_waitcnt lgkmcnt(0)
	v_add_f32_e32 v17, v31, v33
	v_fmamk_f32 v17, v17, 0x3c000000, v199
	v_mul_f32_e32 v20, 0x4f800000, v17
	v_cmp_gt_f32_e32 vcc, s49, v17
	v_ashrrev_i32_e32 v33, 31, v32
	s_nop 0
	v_cndmask_b32_e32 v20, v17, v20, vcc
	v_sqrt_f32_e32 v21, v20
	v_cvt_pk_bf16_f32 v17, v18, v19
	v_lshlrev_b64 v[18:19], 11, v[32:33]
	v_lshl_add_u64 v[18:19], s[10:11], 0, v[18:19]
	v_add_u32_e32 v31, -1, v21
	v_fma_f32 v32, -v31, v21, v20
	v_cmp_ge_f32_e64 s[0:1], 0, v32
	v_add_u32_e32 v32, 1, v21
	v_lshl_add_u64 v[18:19], v[18:19], 0, v[182:183]
	v_cndmask_b32_e64 v31, v21, v31, s[0:1]
	v_fma_f32 v21, -v32, v21, v20
	v_cmp_lt_f32_e64 s[0:1], 0, v21
	global_store_dwordx4 v[18:19], v[14:17], off sc0 sc1
	s_nop 0
	v_cndmask_b32_e64 v21, v31, v32, s[0:1]
	v_mul_f32_e32 v31, 0x37800000, v21
	v_cndmask_b32_e32 v21, v21, v31, vcc
	v_cmp_class_f32_e32 vcc, v20, v200
	v_add_u32_e32 v32, 24, v82
	v_lshl_add_u32 v18, v32, 9, v1
	v_cndmask_b32_e32 v31, v21, v20, vcc
	v_div_scale_f32 v33, s[0:1], v31, v31, s50
	v_rcp_f32_e32 v38, v33
	v_div_scale_f32 v39, vcc, s50, v31, s50
	v_fma_f32 v14, -v33, v38, 1.0
	v_fmac_f32_e32 v38, v14, v38
	ds_read_b128 v[14:17], v18
	ds_read_b128 v[18:21], v18 offset:16
	v_mul_f32_e32 v40, v39, v38
	v_fma_f32 v41, -v33, v40, v39
	v_fmac_f32_e32 v40, v41, v38
	s_waitcnt lgkmcnt(1)
	v_mul_f32_e32 v42, v15, v15
	v_fmac_f32_e32 v42, v14, v14
	v_fmac_f32_e32 v42, v16, v16
	v_fmac_f32_e32 v42, v17, v17
	s_waitcnt lgkmcnt(0)
	v_pk_mul_f32 v[36:37], v[18:19], v[18:19]
	v_pk_mul_f32 v[34:35], v[20:21], v[20:21]
	v_add_f32_e32 v36, v36, v42
	v_add_f32_e32 v36, v37, v36
	v_add_f32_e32 v34, v34, v36
	v_add_f32_e32 v34, v35, v34
	ds_bpermute_b32 v35, v10, v34
	v_fma_f32 v33, -v33, v40, v39
	v_div_fmas_f32 v33, v33, v38, v40
	s_waitcnt lgkmcnt(0)
; __device__ __forceinline__ unsigned cvtpk_s(float lo, float hi) { f32x2_t v = {lo, hi}; bf16x2_t b = __builtin_convertvector(v, bf16x2_t); return __builtin_bit_cast(unsigned, b); }
; __device__ __forceinline__ void attn_unit_d16(const UnitDesc& U, char* shm, float lam, const float* subw) {
;     ...
;         for (int i = 0; i < 8; ++i) { const int row = i * 4 + (lane_e >> 4);
;             const f32x4 v0 = *(const f32x4*)(X + row * 128 + ch * 8), v1 = *(const f32x4*)(X + row * 128 + ch * 8 + 4);
;             float ss = v0[0] * v0[0] + v0[1] * v0[1] + v0[2] * v0[2] + v0[3] * v0[3] + v1[0] * v1[0] + v1[1] * v1[1] + v1[2] * v1[2] + v1[3] * v1[3];
;             ss += __shfl_xor(ss, 1); ss += __shfl_xor(ss, 2); ss += __shfl_xor(ss, 4); ss += __shfl_xor(ss, 8);
;             const float rs = (1.0f - LAMBDA_INIT) / sqrtf(ss * (1.0f / 128.0f) + EPS);
;             u32x4 w; w.x = cvtpk_s(v0[0] * rs * w0[0], v0[1] * rs * w0[1]); w.y = cvtpk_s(v0[2] * rs * w0[2], v0[3] * rs * w0[3]);
;             w.z = cvtpk_s(v1[0] * rs * w1[0], v1[1] * rs * w1[1]); w.w = cvtpk_s(v1[2] * rs * w1[2], v1[3] * rs * w1[3]);
;             *(u32x4*)(U.Ow + (size_t)row * D + ch * 8) = w; }
	v_add_f32_e32 v35, v34, v35
	ds_bpermute_b32 v36, v11, v35
	v_div_fixup_f32 v34, v33, v31, s50
	v_pk_mul_f32 v[22:23], v[22:23], v[34:35] op_sel_hi:[1,0]
	v_pk_mul_f32 v[24:25], v[24:25], v[34:35] op_sel_hi:[1,0]
	v_pk_mul_f32 v[22:23], v[6:7], v[22:23]
	s_waitcnt lgkmcnt(0)
	v_add_f32_e32 v31, v35, v36
	ds_bpermute_b32 v33, v12, v31
	v_pk_mul_f32 v[24:25], v[8:9], v[24:25]
	v_cvt_pk_bf16_f32 v22, v22, v23
	v_cvt_pk_bf16_f32 v23, v24, v25
	v_pk_mul_f32 v[24:25], v[26:27], v[34:35] op_sel_hi:[1,0]
	s_waitcnt lgkmcnt(0)
	v_add_f32_e32 v31, v31, v33
	ds_bpermute_b32 v33, v13, v31
	v_pk_mul_f32 v[24:25], v[2:3], v[24:25]
	v_pk_mul_f32 v[26:27], v[28:29], v[34:35] op_sel_hi:[1,0]
	v_cvt_pk_bf16_f32 v24, v24, v25
	v_pk_mul_f32 v[26:27], v[4:5], v[26:27]
	s_waitcnt lgkmcnt(0)
	v_add_f32_e32 v25, v31, v33
	v_fmamk_f32 v25, v25, 0x3c000000, v199
	v_mul_f32_e32 v28, 0x4f800000, v25
	v_cmp_gt_f32_e32 vcc, s49, v25
	v_ashrrev_i32_e32 v31, 31, v30
	s_nop 0
	v_cndmask_b32_e32 v28, v25, v28, vcc
	v_sqrt_f32_e32 v29, v28
	v_cvt_pk_bf16_f32 v25, v26, v27
	v_lshlrev_b64 v[26:27], 11, v[30:31]
	v_lshl_add_u64 v[26:27], s[10:11], 0, v[26:27]
	v_add_u32_e32 v30, -1, v29
	v_fma_f32 v31, -v30, v29, v28
	v_cmp_ge_f32_e64 s[0:1], 0, v31
	v_add_u32_e32 v31, 1, v29
	v_lshl_add_u64 v[26:27], v[26:27], 0, v[182:183]
	v_cndmask_b32_e64 v30, v29, v30, s[0:1]
	v_fma_f32 v29, -v31, v29, v28
	v_cmp_lt_f32_e64 s[0:1], 0, v29
	global_store_dwordx4 v[26:27], v[22:25], off sc0 sc1
	s_nop 0
	v_cndmask_b32_e64 v29, v30, v31, s[0:1]
	v_mul_f32_e32 v30, 0x37800000, v29
	v_cndmask_b32_e32 v29, v29, v30, vcc
	v_cmp_class_f32_e32 vcc, v28, v200
	v_add_u32_e32 v30, 28, v82
	v_lshl_add_u32 v1, v30, 9, v1
	v_cndmask_b32_e32 v31, v29, v28, vcc
	v_div_scale_f32 v33, s[0:1], v31, v31, s50
	v_rcp_f32_e32 v38, v33
	ds_read_b128 v[26:29], v1 offset:16
	v_div_scale_f32 v39, vcc, s50, v31, s50
	v_fma_f32 v22, -v33, v38, 1.0
	v_fmac_f32_e32 v38, v22, v38
	ds_read_b128 v[22:25], v1
	s_waitcnt lgkmcnt(1)
	v_pk_mul_f32 v[36:37], v[26:27], v[26:27]
	v_pk_mul_f32 v[34:35], v[28:29], v[28:29]
	v_mul_f32_e32 v40, v39, v38
	v_fma_f32 v41, -v33, v40, v39
	s_waitcnt lgkmcnt(0)
	v_mul_f32_e32 v1, v23, v23
	v_fmac_f32_e32 v1, v22, v22
	v_fmac_f32_e32 v1, v24, v24
	v_fmac_f32_e32 v1, v25, v25
	v_add_f32_e32 v1, v36, v1
	v_add_f32_e32 v1, v37, v1
	v_add_f32_e32 v1, v34, v1
	v_add_f32_e32 v1, v35, v1
	ds_bpermute_b32 v10, v10, v1
	v_fmac_f32_e32 v40, v41, v38
	v_fma_f32 v33, -v33, v40, v39
	v_div_fmas_f32 v33, v33, v38, v40
	v_div_fixup_f32 v34, v33, v31, s50
	s_waitcnt lgkmcnt(0)
	v_add_f32_e32 v1, v1, v10
	ds_bpermute_b32 v35, v11, v1
	v_ashrrev_i32_e32 v33, 31, v32
	v_ashrrev_i32_e32 v31, 31, v30
	s_waitcnt lgkmcnt(0)
	v_add_f32_e32 v1, v1, v35
	ds_bpermute_b32 v12, v12, v1
	v_pk_mul_f32 v[10:11], v[14:15], v[34:35] op_sel_hi:[1,0]
	v_pk_mul_f32 v[14:15], v[16:17], v[34:35] op_sel_hi:[1,0]
	v_pk_mul_f32 v[10:11], v[6:7], v[10:11]
	v_pk_mul_f32 v[14:15], v[8:9], v[14:15]
	s_waitcnt lgkmcnt(0)
	v_add_f32_e32 v1, v1, v12
	ds_bpermute_b32 v16, v13, v1
	v_cvt_pk_bf16_f32 v10, v10, v11
	v_cvt_pk_bf16_f32 v11, v14, v15
	v_pk_mul_f32 v[14:15], v[18:19], v[34:35] op_sel_hi:[1,0]
	s_waitcnt lgkmcnt(0)
	v_add_f32_e32 v1, v1, v16
	v_pk_mul_f32 v[12:13], v[2:3], v[14:15]
	v_fmamk_f32 v1, v1, 0x3c000000, v199
	v_cvt_pk_bf16_f32 v12, v12, v13
	v_mul_f32_e32 v13, 0x4f800000, v1
	v_cmp_gt_f32_e32 vcc, s49, v1
	v_pk_mul_f32 v[14:15], v[20:21], v[34:35] op_sel_hi:[1,0]
	s_nop 0
	v_cndmask_b32_e32 v1, v1, v13, vcc
	v_sqrt_f32_e32 v16, v1
	v_pk_mul_f32 v[14:15], v[4:5], v[14:15]
	v_add_u32_e32 v17, -1, v16
	v_fma_f32 v18, -v17, v16, v1
	v_cmp_ge_f32_e64 s[0:1], 0, v18
	v_add_u32_e32 v18, 1, v16
	v_cvt_pk_bf16_f32 v13, v14, v15
	v_cndmask_b32_e64 v17, v16, v17, s[0:1]
	v_fma_f32 v16, -v18, v16, v1
	v_cmp_lt_f32_e64 s[0:1], 0, v16
	v_lshlrev_b64 v[14:15], 11, v[32:33]
	v_lshl_add_u64 v[14:15], s[10:11], 0, v[14:15]
	v_cndmask_b32_e64 v16, v17, v18, s[0:1]
	v_mul_f32_e32 v17, 0x37800000, v16
	v_cndmask_b32_e32 v16, v16, v17, vcc
	v_cmp_class_f32_e32 vcc, v1, v200
	v_lshl_add_u64 v[14:15], v[14:15], 0, v[182:183]
	global_store_dwordx4 v[14:15], v[10:13], off sc0 sc1
	v_cndmask_b32_e32 v1, v16, v1, vcc
	v_div_scale_f32 v16, s[0:1], v1, v1, s50
	v_rcp_f32_e32 v17, v16
	s_nop 0
	v_fma_f32 v10, -v16, v17, 1.0
	v_fmac_f32_e32 v17, v10, v17
	v_div_scale_f32 v10, vcc, s50, v1, s50
	v_mul_f32_e32 v11, v10, v17
	v_fma_f32 v12, -v16, v11, v10
	v_fmac_f32_e32 v11, v12, v17
	v_fma_f32 v10, -v16, v11, v10
	v_div_fmas_f32 v10, v10, v17, v11
	v_div_fixup_f32 v10, v10, v1, s50
	v_pk_mul_f32 v[12:13], v[22:23], v[10:11] op_sel_hi:[1,0]
	s_nop 0
	v_pk_mul_f32 v[6:7], v[6:7], v[12:13]
	v_pk_mul_f32 v[12:13], v[24:25], v[10:11] op_sel_hi:[1,0]
	v_cvt_pk_bf16_f32 v6, v6, v7
	v_pk_mul_f32 v[8:9], v[8:9], v[12:13]
	s_nop 0
	v_cvt_pk_bf16_f32 v7, v8, v9
	v_pk_mul_f32 v[8:9], v[26:27], v[10:11] op_sel_hi:[1,0]
	s_nop 0
	v_pk_mul_f32 v[2:3], v[2:3], v[8:9]
	s_nop 0
	v_cvt_pk_bf16_f32 v8, v2, v3
	v_pk_mul_f32 v[2:3], v[28:29], v[10:11] op_sel_hi:[1,0]
	s_nop 0
	v_pk_mul_f32 v[2:3], v[4:5], v[2:3]
	s_nop 0
	v_cvt_pk_bf16_f32 v9, v2, v3
	v_lshlrev_b64 v[2:3], 11, v[30:31]
	v_lshl_add_u64 v[2:3], s[10:11], 0, v[2:3]
	v_lshl_add_u64 v[2:3], v[2:3], 0, v[182:183]
	global_store_dwordx4 v[2:3], v[6:9], off sc0 sc1
	s_branch .LBB0_425

; __device__ __forceinline__ unsigned cvt_pk_bf16(float lo, float hi) { unsigned r; asm volatile("v_cvt_pk_bf16_f32 %0, %1, %2" : "=v"(r) : "v"(lo), "v"(hi)); return r; }
;     __device__ __forceinline__ void operator()(const f32x4 (&acc)[2][2][4][2], const Unit& u, int wr, int wc, int fr, int fq) const {
; #pragma unroll
;         for (int ai = 0; ai < 2; ++ai)
; #pragma unroll
;             for (int m = 0; m < 4; ++m) {
;                 const int row = u.pm * BM + ai * HALF + wr * 64 + m * 16 + fr;
;                 const float* xr = xrow(xp, xs, row);
; #pragma unroll
;                 for (int bj = 0; bj < 2; ++bj) {
;                     const int col = u.pn * BM + bj * HALF + wc * 32 + 8 * fq;
;                     const f32x4 x0 = *(const f32x4*)(xr + col), x1v = *(const f32x4*)(xr + col + 4);
;                     const f32x4 v0 = acc[ai][bj][m][0] + x0, v1 = acc[ai][bj][m][1] + x1v;
;                     u32x4 w; w.x = cvt_pk_bf16(v0[0], v0[1]); w.y = cvt_pk_bf16(v0[2], v0[3]); w.z = cvt_pk_bf16(v1[0], v1[1]); w.w = cvt_pk_bf16(v1[2], v1[3]);
;                     *(u32x4*)(X1B + (size_t)row * D + col) = w;
;                 }
;             }
.LBB0_516:
	v_lshl_add_u32 v144, s26, 8, v150
	v_add_u32_e32 v148, 0xffffc000, v144
	v_ashrrev_i32_e32 v145, 31, v144
	v_cmp_gt_i32_e32 vcc, s41, v144
	v_lshl_or_b32 v146, s48, 8, v152
	v_mov_b32_e32 v156, s19
	v_cndmask_b32_e32 v149, 0, v145, vcc
	v_cndmask_b32_e32 v148, v148, v144, vcc
	v_mov_b32_e32 v157, s17
	v_mov_b32_e32 v158, s18
	v_mov_b32_e32 v159, s16
	v_ashrrev_i32_e32 v147, 31, v146
	v_cndmask_b32_e32 v161, v156, v157, vcc
	v_cndmask_b32_e32 v160, v158, v159, vcc
	v_lshlrev_b64 v[148:149], 12, v[148:149]
	v_lshl_add_u64 v[160:161], v[160:161], 0, v[148:149]
	v_lshlrev_b64 v[148:149], 2, v[146:147]
	v_lshl_add_u64 v[168:169], v[160:161], 0, v[148:149]
	global_load_dwordx4 v[160:163], v[168:169], off
	global_load_dwordx4 v[164:167], v[168:169], off offset:16
	v_lshlrev_b64 v[170:171], 11, v[144:145]
	v_lshlrev_b64 v[146:147], 1, v[146:147]
	v_lshl_add_u64 v[170:171], s[20:21], 0, v[170:171]
	v_lshl_add_u64 v[170:171], v[170:171], 0, v[146:147]
	v_add_u32_e32 v145, 0xffffc010, v144
	s_waitcnt vmcnt(0)
	v_pk_add_f32 v[124:125], v[124:125], v[160:161]
	v_pk_add_f32 v[160:161], v[122:123], v[166:167]
	v_pk_add_f32 v[122:123], v[120:121], v[164:165]
	v_pk_add_f32 v[126:127], v[126:127], v[162:163]
	v_cvt_pk_bf16_f32 v120, v124, v125
	s_nop 0
	v_cvt_pk_bf16_f32 v121, v126, v127
	v_cvt_pk_bf16_f32 v122, v122, v123
	v_cvt_pk_bf16_f32 v123, v160, v161
	global_store_dwordx4 v[170:171], v[120:123], off sc0 sc1
	global_load_dwordx4 v[120:123], v[168:169], off offset:512
	s_nop 0
	global_load_dwordx4 v[124:127], v[168:169], off offset:528
	v_or_b32_e32 v160, 16, v144
	v_ashrrev_i32_e32 v161, 31, v160
	v_cmp_gt_i32_e32 vcc, s41, v160
	s_waitcnt vmcnt(1)
	v_pk_add_f32 v[116:117], v[116:117], v[120:121]
	v_cndmask_b32_e32 v163, 0, v161, vcc
	v_cndmask_b32_e32 v162, v145, v160, vcc
	v_cndmask_b32_e32 v165, v156, v157, vcc
	v_cndmask_b32_e32 v164, v158, v159, vcc
	v_lshlrev_b64 v[162:163], 12, v[162:163]
	v_lshl_add_u64 v[162:163], v[164:165], 0, v[162:163]
	s_waitcnt vmcnt(0)
	v_pk_add_f32 v[120:121], v[114:115], v[126:127]
	v_pk_add_f32 v[114:115], v[112:113], v[124:125]
	v_lshl_add_u64 v[162:163], v[162:163], 0, v[148:149]
	v_pk_add_f32 v[118:119], v[118:119], v[122:123]
	v_cvt_pk_bf16_f32 v112, v116, v117
	s_nop 0
	v_cvt_pk_bf16_f32 v113, v118, v119
	v_cvt_pk_bf16_f32 v114, v114, v115
	v_cvt_pk_bf16_f32 v115, v120, v121
	global_store_dwordx4 v[170:171], v[112:115], off offset:256 sc0 sc1
	global_load_dwordx4 v[112:115], v[162:163], off
	s_nop 0
	global_load_dwordx4 v[116:119], v[162:163], off offset:16
	v_lshlrev_b64 v[120:121], 11, v[160:161]
	v_lshl_add_u64 v[120:121], s[20:21], 0, v[120:121]
	v_lshl_add_u64 v[120:121], v[120:121], 0, v[146:147]
	s_waitcnt vmcnt(1)
	v_pk_add_f32 v[108:109], v[108:109], v[112:113]
	s_waitcnt vmcnt(0)
	v_pk_add_f32 v[112:113], v[106:107], v[118:119]
	v_pk_add_f32 v[106:107], v[104:105], v[116:117]
	v_pk_add_f32 v[110:111], v[110:111], v[114:115]
	v_cvt_pk_bf16_f32 v104, v108, v109
	v_add_u32_e32 v114, 0xffffc020, v144
	v_cvt_pk_bf16_f32 v105, v110, v111
	v_cvt_pk_bf16_f32 v106, v106, v107
	v_cvt_pk_bf16_f32 v107, v112, v113
	global_store_dwordx4 v[120:121], v[104:107], off sc0 sc1
	global_load_dwordx4 v[104:107], v[162:163], off offset:512
	s_nop 0
	global_load_dwordx4 v[108:111], v[162:163], off offset:528
	v_or_b32_e32 v112, 32, v144
	v_ashrrev_i32_e32 v113, 31, v112
	v_cmp_gt_i32_e32 vcc, s41, v112
	s_waitcnt vmcnt(1)
	v_pk_add_f32 v[100:101], v[100:101], v[104:105]
	v_cndmask_b32_e32 v115, 0, v113, vcc
	v_cndmask_b32_e32 v114, v114, v112, vcc
	v_cndmask_b32_e32 v117, v156, v157, vcc
	v_cndmask_b32_e32 v116, v158, v159, vcc
	v_lshlrev_b64 v[114:115], 12, v[114:115]
	v_lshl_add_u64 v[114:115], v[116:117], 0, v[114:115]
	s_waitcnt vmcnt(0)
	v_pk_add_f32 v[104:105], v[98:99], v[110:111]
	v_pk_add_f32 v[98:99], v[96:97], v[108:109]
	v_lshl_add_u64 v[114:115], v[114:115], 0, v[148:149]
	v_pk_add_f32 v[102:103], v[102:103], v[106:107]
	v_cvt_pk_bf16_f32 v96, v100, v101
	s_nop 0
	v_cvt_pk_bf16_f32 v97, v102, v103
	v_cvt_pk_bf16_f32 v98, v98, v99
	v_cvt_pk_bf16_f32 v99, v104, v105
	global_store_dwordx4 v[120:121], v[96:99], off offset:256 sc0 sc1
	global_load_dwordx4 v[96:99], v[114:115], off
	s_nop 0
	global_load_dwordx4 v[100:103], v[114:115], off offset:16
	v_lshlrev_b64 v[104:105], 11, v[112:113]
	v_lshl_add_u64 v[104:105], s[20:21], 0, v[104:105]
	v_lshl_add_u64 v[104:105], v[104:105], 0, v[146:147]
	s_waitcnt vmcnt(1)
	v_pk_add_f32 v[92:93], v[92:93], v[96:97]
	s_waitcnt vmcnt(0)
	v_pk_add_f32 v[96:97], v[90:91], v[102:103]
	v_pk_add_f32 v[90:91], v[88:89], v[100:101]
	v_pk_add_f32 v[94:95], v[94:95], v[98:99]
	v_cvt_pk_bf16_f32 v88, v92, v93
	v_add_u32_e32 v98, 0xffffc030, v144
	v_cvt_pk_bf16_f32 v89, v94, v95
	v_cvt_pk_bf16_f32 v90, v90, v91
	v_cvt_pk_bf16_f32 v91, v96, v97
	global_store_dwordx4 v[104:105], v[88:91], off sc0 sc1
	global_load_dwordx4 v[88:91], v[114:115], off offset:512
	s_nop 0
	global_load_dwordx4 v[92:95], v[114:115], off offset:528
	v_or_b32_e32 v96, 48, v144
	v_ashrrev_i32_e32 v97, 31, v96
	v_cmp_gt_i32_e32 vcc, s41, v96
	s_waitcnt vmcnt(1)
	v_pk_add_f32 v[84:85], v[84:85], v[88:89]
	v_cndmask_b32_e32 v99, 0, v97, vcc
	v_cndmask_b32_e32 v98, v98, v96, vcc
	v_cndmask_b32_e32 v101, v156, v157, vcc
	v_cndmask_b32_e32 v100, v158, v159, vcc
	v_lshlrev_b64 v[98:99], 12, v[98:99]
	v_lshl_add_u64 v[98:99], v[100:101], 0, v[98:99]
	s_waitcnt vmcnt(0)
; __device__ __forceinline__ unsigned cvt_pk_bf16(float lo, float hi) { unsigned r; asm volatile("v_cvt_pk_bf16_f32 %0, %1, %2" : "=v"(r) : "v"(lo), "v"(hi)); return r; }
;     __device__ __forceinline__ void operator()(const f32x4 (&acc)[2][2][4][2], const Unit& u, int wr, int wc, int fr, int fq) const {
; #pragma unroll
;         for (int ai = 0; ai < 2; ++ai)
; #pragma unroll
;             for (int m = 0; m < 4; ++m) {
;                 const int row = u.pm * BM + ai * HALF + wr * 64 + m * 16 + fr;
;                 const float* xr = xrow(xp, xs, row);
; #pragma unroll
;                 for (int bj = 0; bj < 2; ++bj) {
;                     const int col = u.pn * BM + bj * HALF + wc * 32 + 8 * fq;
;                     const f32x4 x0 = *(const f32x4*)(xr + col), x1v = *(const f32x4*)(xr + col + 4);
;                     const f32x4 v0 = acc[ai][bj][m][0] + x0, v1 = acc[ai][bj][m][1] + x1v;
;                     u32x4 w; w.x = cvt_pk_bf16(v0[0], v0[1]); w.y = cvt_pk_bf16(v0[2], v0[3]); w.z = cvt_pk_bf16(v1[0], v1[1]); w.w = cvt_pk_bf16(v1[2], v1[3]);
;                     *(u32x4*)(X1B + (size_t)row * D + col) = w;
;                 }
;             }
	v_pk_add_f32 v[88:89], v[82:83], v[94:95]
	v_pk_add_f32 v[82:83], v[80:81], v[92:93]
	v_lshl_add_u64 v[98:99], v[98:99], 0, v[148:149]
	v_pk_add_f32 v[86:87], v[86:87], v[90:91]
	v_cvt_pk_bf16_f32 v80, v84, v85
	s_nop 0
	v_cvt_pk_bf16_f32 v81, v86, v87
	v_cvt_pk_bf16_f32 v82, v82, v83
	v_cvt_pk_bf16_f32 v83, v88, v89
	global_store_dwordx4 v[104:105], v[80:83], off offset:256 sc0 sc1
	global_load_dwordx4 v[80:83], v[98:99], off
	s_nop 0
	global_load_dwordx4 v[84:87], v[98:99], off offset:16
	v_lshlrev_b64 v[88:89], 11, v[96:97]
	v_lshl_add_u64 v[88:89], s[20:21], 0, v[88:89]
	v_lshl_add_u64 v[88:89], v[88:89], 0, v[146:147]
	s_waitcnt vmcnt(1)
	v_pk_add_f32 v[76:77], v[76:77], v[80:81]
	s_waitcnt vmcnt(0)
	v_pk_add_f32 v[80:81], v[74:75], v[86:87]
	v_pk_add_f32 v[74:75], v[72:73], v[84:85]
	v_pk_add_f32 v[78:79], v[78:79], v[82:83]
	v_cvt_pk_bf16_f32 v72, v76, v77
	v_add_u32_e32 v82, 0xffffc080, v144
	v_cvt_pk_bf16_f32 v73, v78, v79
	v_cvt_pk_bf16_f32 v74, v74, v75
	v_cvt_pk_bf16_f32 v75, v80, v81
	global_store_dwordx4 v[88:89], v[72:75], off sc0 sc1
	global_load_dwordx4 v[72:75], v[98:99], off offset:512
	s_nop 0
	global_load_dwordx4 v[76:79], v[98:99], off offset:528
	v_add_u32_e32 v80, 0x80, v144
	v_ashrrev_i32_e32 v81, 31, v80
	v_cmp_gt_i32_e32 vcc, s41, v80
	s_waitcnt vmcnt(1)
	v_pk_add_f32 v[68:69], v[68:69], v[72:73]
	v_cndmask_b32_e32 v83, 0, v81, vcc
	v_cndmask_b32_e32 v82, v82, v80, vcc
	v_cndmask_b32_e32 v85, v156, v157, vcc
	v_cndmask_b32_e32 v84, v158, v159, vcc
	v_lshlrev_b64 v[82:83], 12, v[82:83]
	v_lshl_add_u64 v[82:83], v[84:85], 0, v[82:83]
	s_waitcnt vmcnt(0)
	v_pk_add_f32 v[72:73], v[66:67], v[78:79]
	v_pk_add_f32 v[66:67], v[64:65], v[76:77]
	v_lshl_add_u64 v[82:83], v[82:83], 0, v[148:149]
	v_pk_add_f32 v[70:71], v[70:71], v[74:75]
	v_cvt_pk_bf16_f32 v64, v68, v69
	s_nop 0
	v_cvt_pk_bf16_f32 v65, v70, v71
	v_cvt_pk_bf16_f32 v66, v66, v67
	v_cvt_pk_bf16_f32 v67, v72, v73
	global_store_dwordx4 v[88:89], v[64:67], off offset:256 sc0 sc1
	global_load_dwordx4 v[64:67], v[82:83], off
	s_nop 0
	global_load_dwordx4 v[68:71], v[82:83], off offset:16
	v_lshlrev_b64 v[72:73], 11, v[80:81]
	v_lshl_add_u64 v[72:73], s[20:21], 0, v[72:73]
	v_lshl_add_u64 v[72:73], v[72:73], 0, v[146:147]
	s_waitcnt vmcnt(1)
	v_pk_add_f32 v[60:61], v[60:61], v[64:65]
	s_waitcnt vmcnt(0)
	v_pk_add_f32 v[64:65], v[58:59], v[70:71]
	v_pk_add_f32 v[58:59], v[56:57], v[68:69]
	v_pk_add_f32 v[62:63], v[62:63], v[66:67]
	v_cvt_pk_bf16_f32 v56, v60, v61
	v_add_u32_e32 v66, 0xffffc090, v144
	v_cvt_pk_bf16_f32 v57, v62, v63
	v_cvt_pk_bf16_f32 v58, v58, v59
	v_cvt_pk_bf16_f32 v59, v64, v65
	global_store_dwordx4 v[72:73], v[56:59], off sc0 sc1
	global_load_dwordx4 v[56:59], v[82:83], off offset:512
	s_nop 0
	global_load_dwordx4 v[60:63], v[82:83], off offset:528
	v_add_u32_e32 v64, 0x90, v144
	v_ashrrev_i32_e32 v65, 31, v64
	v_cmp_gt_i32_e32 vcc, s41, v64
	s_waitcnt vmcnt(1)
	v_pk_add_f32 v[52:53], v[52:53], v[56:57]
	v_cndmask_b32_e32 v67, 0, v65, vcc
	v_cndmask_b32_e32 v66, v66, v64, vcc
	v_cndmask_b32_e32 v69, v156, v157, vcc
	v_cndmask_b32_e32 v68, v158, v159, vcc
	v_lshlrev_b64 v[66:67], 12, v[66:67]
	v_lshl_add_u64 v[66:67], v[68:69], 0, v[66:67]
	s_waitcnt vmcnt(0)
	v_pk_add_f32 v[56:57], v[50:51], v[62:63]
	v_pk_add_f32 v[50:51], v[48:49], v[60:61]
	v_lshl_add_u64 v[66:67], v[66:67], 0, v[148:149]
	v_pk_add_f32 v[54:55], v[54:55], v[58:59]
	v_cvt_pk_bf16_f32 v48, v52, v53
	s_nop 0
	v_cvt_pk_bf16_f32 v49, v54, v55
	v_cvt_pk_bf16_f32 v50, v50, v51
	v_cvt_pk_bf16_f32 v51, v56, v57
	global_store_dwordx4 v[72:73], v[48:51], off offset:256 sc0 sc1
	global_load_dwordx4 v[48:51], v[66:67], off
	s_nop 0
	global_load_dwordx4 v[52:55], v[66:67], off offset:16
	v_lshlrev_b64 v[56:57], 11, v[64:65]
	v_lshl_add_u64 v[56:57], s[20:21], 0, v[56:57]
	v_lshl_add_u64 v[56:57], v[56:57], 0, v[146:147]
	s_waitcnt vmcnt(1)
	v_pk_add_f32 v[44:45], v[44:45], v[48:49]
	s_waitcnt vmcnt(0)
; __device__ __forceinline__ unsigned cvt_pk_bf16(float lo, float hi) { unsigned r; asm volatile("v_cvt_pk_bf16_f32 %0, %1, %2" : "=v"(r) : "v"(lo), "v"(hi)); return r; }
;     __device__ __forceinline__ void operator()(const f32x4 (&acc)[2][2][4][2], const Unit& u, int wr, int wc, int fr, int fq) const {
; #pragma unroll
;         for (int ai = 0; ai < 2; ++ai)
; #pragma unroll
;             for (int m = 0; m < 4; ++m) {
;                 const int row = u.pm * BM + ai * HALF + wr * 64 + m * 16 + fr;
;                 const float* xr = xrow(xp, xs, row);
; #pragma unroll
;                 for (int bj = 0; bj < 2; ++bj) {
;                     const int col = u.pn * BM + bj * HALF + wc * 32 + 8 * fq;
;                     const f32x4 x0 = *(const f32x4*)(xr + col), x1v = *(const f32x4*)(xr + col + 4);
;                     const f32x4 v0 = acc[ai][bj][m][0] + x0, v1 = acc[ai][bj][m][1] + x1v;
;                     u32x4 w; w.x = cvt_pk_bf16(v0[0], v0[1]); w.y = cvt_pk_bf16(v0[2], v0[3]); w.z = cvt_pk_bf16(v1[0], v1[1]); w.w = cvt_pk_bf16(v1[2], v1[3]);
;                     *(u32x4*)(X1B + (size_t)row * D + col) = w;
;                 }
;             }
	v_pk_add_f32 v[48:49], v[42:43], v[54:55]
	v_pk_add_f32 v[42:43], v[40:41], v[52:53]
	v_pk_add_f32 v[46:47], v[46:47], v[50:51]
	v_cvt_pk_bf16_f32 v40, v44, v45
	v_add_u32_e32 v50, 0xffffc0a0, v144
	v_cvt_pk_bf16_f32 v41, v46, v47
	v_cvt_pk_bf16_f32 v42, v42, v43
	v_cvt_pk_bf16_f32 v43, v48, v49
	global_store_dwordx4 v[56:57], v[40:43], off sc0 sc1
	global_load_dwordx4 v[40:43], v[66:67], off offset:512
	s_nop 0
	global_load_dwordx4 v[44:47], v[66:67], off offset:528
	v_add_u32_e32 v48, 0xa0, v144
	v_ashrrev_i32_e32 v49, 31, v48
	v_cmp_gt_i32_e32 vcc, s41, v48
	s_waitcnt vmcnt(1)
	v_pk_add_f32 v[36:37], v[36:37], v[40:41]
	v_cndmask_b32_e32 v51, 0, v49, vcc
	v_cndmask_b32_e32 v50, v50, v48, vcc
	v_cndmask_b32_e32 v53, v156, v157, vcc
	v_cndmask_b32_e32 v52, v158, v159, vcc
	v_lshlrev_b64 v[50:51], 12, v[50:51]
	v_lshl_add_u64 v[50:51], v[52:53], 0, v[50:51]
	s_waitcnt vmcnt(0)
	v_pk_add_f32 v[40:41], v[34:35], v[46:47]
	v_pk_add_f32 v[34:35], v[32:33], v[44:45]
	v_lshl_add_u64 v[50:51], v[50:51], 0, v[148:149]
	v_pk_add_f32 v[38:39], v[38:39], v[42:43]
	v_cvt_pk_bf16_f32 v32, v36, v37
	s_nop 0
	v_cvt_pk_bf16_f32 v33, v38, v39
	v_cvt_pk_bf16_f32 v34, v34, v35
	v_cvt_pk_bf16_f32 v35, v40, v41
	global_store_dwordx4 v[56:57], v[32:35], off offset:256 sc0 sc1
	global_load_dwordx4 v[32:35], v[50:51], off
	s_nop 0
	global_load_dwordx4 v[36:39], v[50:51], off offset:16
	v_lshlrev_b64 v[40:41], 11, v[48:49]
	v_lshl_add_u64 v[40:41], s[20:21], 0, v[40:41]
	v_lshl_add_u64 v[40:41], v[40:41], 0, v[146:147]
	s_waitcnt vmcnt(1)
	v_pk_add_f32 v[28:29], v[28:29], v[32:33]
	s_waitcnt vmcnt(0)
	v_pk_add_f32 v[32:33], v[26:27], v[38:39]
	v_pk_add_f32 v[26:27], v[24:25], v[36:37]
	v_pk_add_f32 v[30:31], v[30:31], v[34:35]
	v_cvt_pk_bf16_f32 v24, v28, v29
	v_add_u32_e32 v34, 0xffffc0b0, v144
	v_cvt_pk_bf16_f32 v25, v30, v31
	v_cvt_pk_bf16_f32 v26, v26, v27
	v_cvt_pk_bf16_f32 v27, v32, v33
	global_store_dwordx4 v[40:41], v[24:27], off sc0 sc1
	global_load_dwordx4 v[24:27], v[50:51], off offset:512
	s_nop 0
	global_load_dwordx4 v[28:31], v[50:51], off offset:528
	v_add_u32_e32 v32, 0xb0, v144
	v_ashrrev_i32_e32 v33, 31, v32
	v_cmp_gt_i32_e32 vcc, s41, v32
	s_waitcnt vmcnt(1)
	v_pk_add_f32 v[20:21], v[20:21], v[24:25]
	v_cndmask_b32_e32 v35, 0, v33, vcc
	v_cndmask_b32_e32 v34, v34, v32, vcc
	v_cndmask_b32_e32 v37, v156, v157, vcc
	v_cndmask_b32_e32 v36, v158, v159, vcc
	v_lshlrev_b64 v[34:35], 12, v[34:35]
	v_lshl_add_u64 v[34:35], v[36:37], 0, v[34:35]
	s_waitcnt vmcnt(0)
	v_pk_add_f32 v[24:25], v[18:19], v[30:31]
	v_pk_add_f32 v[18:19], v[16:17], v[28:29]
	v_lshl_add_u64 v[34:35], v[34:35], 0, v[148:149]
	v_pk_add_f32 v[22:23], v[22:23], v[26:27]
	v_cvt_pk_bf16_f32 v16, v20, v21
	s_andn2_b64 vcc, exec, s[0:1]
	v_cvt_pk_bf16_f32 v17, v22, v23
	v_cvt_pk_bf16_f32 v18, v18, v19
	v_cvt_pk_bf16_f32 v19, v24, v25
	global_store_dwordx4 v[40:41], v[16:19], off offset:256 sc0 sc1
	global_load_dwordx4 v[16:19], v[34:35], off
	s_nop 0
	global_load_dwordx4 v[20:23], v[34:35], off offset:16
	v_lshlrev_b64 v[24:25], 11, v[32:33]
	v_lshl_add_u64 v[24:25], s[20:21], 0, v[24:25]
	v_lshl_add_u64 v[24:25], v[24:25], 0, v[146:147]
	s_mov_b64 s[0:1], -1
	s_waitcnt vmcnt(1)
	v_pk_add_f32 v[12:13], v[12:13], v[16:17]
	s_waitcnt vmcnt(0)
	v_pk_add_f32 v[16:17], v[10:11], v[22:23]
	v_pk_add_f32 v[10:11], v[8:9], v[20:21]
	v_pk_add_f32 v[14:15], v[14:15], v[18:19]
	v_cvt_pk_bf16_f32 v8, v12, v13
	s_nop 0
	v_cvt_pk_bf16_f32 v9, v14, v15
	v_cvt_pk_bf16_f32 v10, v10, v11
	v_cvt_pk_bf16_f32 v11, v16, v17
	global_store_dwordx4 v[24:25], v[8:11], off sc0 sc1
	global_load_dwordx4 v[8:11], v[34:35], off offset:512
	s_nop 0
	global_load_dwordx4 v[12:15], v[34:35], off offset:528
	s_waitcnt vmcnt(1)
	v_pk_add_f32 v[4:5], v[4:5], v[8:9]
	s_waitcnt vmcnt(0)
	v_pk_add_f32 v[8:9], v[2:3], v[14:15]
	v_pk_add_f32 v[2:3], v[0:1], v[12:13]
	v_pk_add_f32 v[6:7], v[6:7], v[10:11]
	v_cvt_pk_bf16_f32 v0, v4, v5
	s_nop 0
	v_cvt_pk_bf16_f32 v1, v6, v7
	v_cvt_pk_bf16_f32 v2, v2, v3
	v_cvt_pk_bf16_f32 v3, v8, v9
	global_store_dwordx4 v[24:25], v[0:3], off offset:256 sc0 sc1
	s_cbranch_vccnz .LBB0_509
	s_andn2_b64 vcc, exec, s[4:5]
	s_cbranch_vccnz .LBB0_508
	s_barrier
	s_branch .LBB0_508

;     __device__ __forceinline__ void fused(f32x4 (&acc)[2][2][4][2], const Unit& u, int wr, int wc, int fr, int fq, PG8_LAS unsigned char* lds, int wid, int lane) const {
;     ...
;                 if (hw == 0) TOPK_EMIT8(0); else TOPK_EMIT8(8);
.LBB0_576:
	v_lshlrev_b32_e32 v14, 6, v13
	v_lshlrev_b32_e32 v15, 10, v13
	v_lshlrev_b32_e32 v16, 6, v12
	v_lshlrev_b32_e32 v17, 10, v12
	v_lshlrev_b32_e32 v21, 10, v10
	v_and_b32_e32 v14, 0x3c00, v14
	v_and_b32_e32 v15, 0x3c00, v15
	v_and_b32_e32 v16, 0x3c00, v16
	v_and_b32_e32 v17, 0x3c00, v17
	v_lshlrev_b32_e32 v18, 6, v11
	v_lshlrev_b32_e32 v19, 10, v11
	v_lshlrev_b32_e32 v20, 6, v10
	v_and_b32_e32 v21, 0x3c00, v21
	v_add_u32_e32 v14, v72, v14
	v_add_u32_e32 v15, v72, v15
	v_add_u32_e32 v16, v72, v16
	v_add_u32_e32 v17, v72, v17
	v_and_b32_e32 v18, 0x3c00, v18
	v_and_b32_e32 v19, 0x3c00, v19
	v_and_b32_e32 v20, 0x3c00, v20
	v_add_u32_e32 v21, v72, v21
	v_add_u32_e32 v18, v72, v18
	v_add_u32_e32 v19, v72, v19
	v_add_u32_e32 v20, v72, v20
	ds_read_b32 v14, v14
	ds_read_b32 v15, v15 offset:512
	ds_read_b32 v16, v16
	ds_read_b32 v17, v17 offset:512
	ds_read_b32 v22, v18
	ds_read_b32 v23, v19 offset:512
	ds_read_b32 v24, v20
	ds_read_b32 v21, v21 offset:512
	s_waitcnt lgkmcnt(7)
	v_lshlrev_b32_e32 v14, 7, v14
	s_waitcnt lgkmcnt(6)
	v_and_b32_e32 v15, 0x7f, v15
	v_and_b32_e32 v14, 0x3f80, v14
	v_bitop3_b32 v14, v15, s40, v14 bitop3:0x36
	s_waitcnt lgkmcnt(5)
	v_lshlrev_b32_e32 v15, 7, v16
	v_and_b32_e32 v18, 0xffffff00, v13
	s_waitcnt lgkmcnt(4)
	v_and_b32_e32 v13, 0x7f, v17
	v_and_b32_e32 v15, 0x3f80, v15
	v_bitop3_b32 v15, v13, s40, v15 bitop3:0x36
	s_waitcnt lgkmcnt(3)
	v_lshlrev_b32_e32 v13, 7, v22
	v_and_b32_e32 v19, 0xffffff00, v12
	s_waitcnt lgkmcnt(2)
	v_and_b32_e32 v12, 0x7f, v23
	v_and_b32_e32 v13, 0x3f80, v13
	v_bitop3_b32 v16, v12, s40, v13 bitop3:0x36
	s_waitcnt lgkmcnt(1)
	v_lshlrev_b32_e32 v12, 7, v24
	v_and_b32_e32 v20, 0xffffff00, v11
	s_waitcnt lgkmcnt(0)
	v_and_b32_e32 v11, 0x7f, v21
	v_and_b32_e32 v12, 0x3f80, v12
	v_bitop3_b32 v17, v11, s40, v12 bitop3:0x36
	v_and_b32_e32 v21, 0xffffff00, v10
	v_lshlrev_b32_e32 v10, 6, v6
	v_lshlrev_b32_e32 v11, 10, v6
	v_lshlrev_b32_e32 v12, 6, v7
	v_lshlrev_b32_e32 v13, 10, v7
	v_lshlrev_b32_e32 v22, 6, v8
	v_lshlrev_b32_e32 v23, 10, v8
	v_lshlrev_b32_e32 v24, 6, v9
	v_lshlrev_b32_e32 v25, 10, v9
	v_and_b32_e32 v10, 0x3c00, v10
	v_and_b32_e32 v11, 0x3c00, v11
	v_and_b32_e32 v12, 0x3c00, v12
	v_and_b32_e32 v13, 0x3c00, v13
	v_and_b32_e32 v22, 0x3c00, v22
	v_and_b32_e32 v23, 0x3c00, v23
	v_and_b32_e32 v24, 0x3c00, v24
	v_and_b32_e32 v25, 0x3c00, v25
	v_add_u32_e32 v10, v72, v10
	v_add_u32_e32 v11, v72, v11
	v_add_u32_e32 v12, v72, v12
	v_add_u32_e32 v13, v72, v13
	v_add_u32_e32 v22, v72, v22
	v_add_u32_e32 v23, v72, v23
	v_add_u32_e32 v24, v72, v24
	v_add_u32_e32 v25, v72, v25
	ds_read_b32 v10, v10
	ds_read_b32 v11, v11 offset:512
	ds_read_b32 v12, v12
	ds_read_b32 v13, v13 offset:512
	ds_read_b32 v22, v22
	ds_read_b32 v23, v23 offset:512
	ds_read_b32 v24, v24
	ds_read_b32 v25, v25 offset:512
	s_waitcnt lgkmcnt(7)
	v_lshlrev_b32_e32 v10, 7, v10
	s_waitcnt lgkmcnt(6)
	v_and_b32_e32 v11, 0x7f, v11
	v_and_b32_e32 v10, 0x3f80, v10
	s_waitcnt lgkmcnt(5)
	v_lshlrev_b32_e32 v12, 7, v12
	v_bitop3_b32 v10, v11, s40, v10 bitop3:0x36
	s_waitcnt lgkmcnt(4)
	v_and_b32_e32 v11, 0x7f, v13
	v_and_b32_e32 v12, 0x3f80, v12
	s_waitcnt lgkmcnt(3)
	v_lshlrev_b32_e32 v13, 7, v22
	v_bitop3_b32 v11, v11, s40, v12 bitop3:0x36
	s_waitcnt lgkmcnt(2)
	v_and_b32_e32 v12, 0x7f, v23
	v_and_b32_e32 v13, 0x3f80, v13
	s_waitcnt lgkmcnt(1)
	v_lshlrev_b32_e32 v22, 7, v24
	v_bitop3_b32 v12, v12, s40, v13 bitop3:0x36
	s_waitcnt lgkmcnt(0)
	v_and_b32_e32 v13, 0x7f, v25
	v_and_b32_e32 v22, 0x3f80, v22
	v_bitop3_b32 v13, v13, s40, v22 bitop3:0x36
	global_store_dwordx4 v[4:5], v[14:17], off sc0 sc1
	global_store_dwordx4 v[4:5], v[10:13], off offset:16 sc0 sc1
	global_store_dwordx4 v[2:3], v[18:21], off sc0 sc1
	s_mov_b64 s[0:1], 16
	v_mov_b32_e32 v14, v6
	v_mov_b32_e32 v15, v7
	v_mov_b32_e32 v16, v8
	v_mov_b32_e32 v17, v9
.LBB0_577:
	v_lshl_add_u64 v[0:1], v[0:1], 2, s[8:9]
	v_and_b32_e32 v5, 0xffffff00, v17
	v_and_b32_e32 v4, 0xffffff00, v16
	v_and_b32_e32 v3, 0xffffff00, v15
	v_and_b32_e32 v2, 0xffffff00, v14
	v_lshl_add_u64 v[0:1], v[0:1], 0, s[0:1]
	global_store_dwordx4 v[0:1], v[2:5], off sc0 sc1

; #define PG8_LAS __attribute__((address_space(3)))
;     __device__ __forceinline__ void fused(f32x4 (&acc)[2][2][4][2], const Unit& u, int wr, int wc, int fr, int fq, PG8_LAS unsigned char* lds, int wid, int lane) const {
;     ...
;             if (tid < 256) {
;                 const int row = tid & 127, hw = tid >> 7;
;                 PG8_LAS const unsigned* l2 = (PG8_LAS const unsigned*)lds;
;                 unsigned T[16], G[16];
; #pragma unroll
;                 for (int i = 0; i < 16; ++i) { T[i] = l2[i * 128 + row]; G[i] = l2[(16 + i) * 128 + row]; }
;                 merge16_desc(T, G);
;                 const size_t o = ((size_t)h * M + (size_t)(u.pm * BM + ai * HALF + row)) * 16;
;     ...
;                 if (hw == 0) TOPK_EMIT8(0); else TOPK_EMIT8(8);
.LBB0_599:
	s_or_b64 exec, exec, s[18:19]
	s_mul_hi_i32 s19, s11, 0xc000
	s_mul_i32 s18, s11, 0xc000
	v_lshl_add_u32 v72, v166, 2, s39
	v_lshl_or_b32 v64, s17, 8, v140
	s_waitcnt lgkmcnt(0)
	s_barrier
	s_and_saveexec_b64 s[22:23], s[0:1]
	s_cbranch_execz .LBB0_606
	ds_read2st64_b32 v[66:67], v83 offset1:2
	ds_read2st64_b32 v[68:69], v83 offset0:32 offset1:34
	ds_read2st64_b32 v[70:71], v83 offset0:4 offset1:6
	ds_read2st64_b32 v[74:75], v83 offset0:36 offset1:38
	ds_read2st64_b32 v[76:77], v83 offset0:8 offset1:10
	ds_read2st64_b32 v[78:79], v83 offset0:40 offset1:42
	ds_read2st64_b32 v[80:81], v83 offset0:12 offset1:14
	ds_read2st64_b32 v[94:95], v83 offset0:44 offset1:46
	ds_read2st64_b32 v[96:97], v83 offset0:16 offset1:18
	ds_read2st64_b32 v[98:99], v83 offset0:48 offset1:50
	ds_read2st64_b32 v[100:101], v83 offset0:20 offset1:22
	ds_read2st64_b32 v[102:103], v83 offset0:60 offset1:62
	ds_read2st64_b32 v[108:109], v83 offset0:52 offset1:54
	ds_read2st64_b32 v[110:111], v83 offset0:56 offset1:58
	ds_read2st64_b32 v[112:113], v83 offset0:24 offset1:26
	ds_read2st64_b32 v[114:115], v83 offset0:28 offset1:30
	s_waitcnt lgkmcnt(4)
	v_max_f32 v65, v66, v103
	v_max_f32 v66, v67, v102
	s_waitcnt lgkmcnt(2)
	v_max_f32 v67, v70, v111
	v_max_f32 v70, v71, v110
	v_max_f32 v71, v76, v109
	v_max_f32 v73, v77, v108
	v_max_f32 v76, v80, v99
	v_max_f32 v77, v81, v98
	v_max_f32 v80, v96, v95
	v_max_f32 v81, v97, v94
	v_max_f32 v79, v100, v79
	v_max_f32 v78, v101, v78
	s_waitcnt lgkmcnt(1)
	v_max_f32 v75, v112, v75
	v_max_f32 v74, v113, v74
	s_waitcnt lgkmcnt(0)
	v_max_f32 v69, v114, v69
	v_max_f32 v68, v115, v68
	v_max_f32 v94, v65, v80
	v_min_f32 v65, v65, v80
	v_max_f32 v80, v66, v81
	v_min_f32 v66, v66, v81
	v_max_f32 v81, v67, v79
	v_min_f32 v67, v67, v79
	v_max_f32 v79, v70, v78
	v_min_f32 v70, v70, v78
	v_max_f32 v78, v71, v75
	v_min_f32 v71, v71, v75
	v_max_f32 v75, v73, v74
	v_min_f32 v73, v73, v74
	s_nop 0
	v_max_f32 v74, v76, v69
	v_min_f32 v69, v76, v69
	v_max_f32 v76, v77, v68
	v_min_f32 v68, v77, v68
	v_max_f32 v77, v94, v78
	v_min_f32 v78, v94, v78
	v_max_f32 v94, v80, v75
	v_min_f32 v75, v80, v75
	s_nop 0
	v_max_f32 v80, v81, v74
	v_min_f32 v74, v81, v74
	v_max_f32 v81, v79, v76
	v_min_f32 v76, v79, v76
	v_max_f32 v79, v65, v71
	v_min_f32 v65, v65, v71
	v_max_f32 v71, v66, v73
	v_min_f32 v66, v66, v73
	v_max_f32 v73, v67, v69
	v_min_f32 v67, v67, v69
	v_max_f32 v69, v70, v68
	s_nop 0
	v_max_f32 v95, v94, v81
	v_min_f32 v81, v94, v81
	v_max_f32 v94, v78, v74
	v_min_f32 v96, v78, v74
	v_max_f32 v74, v75, v76
	v_min_f32 v76, v75, v76
	v_max_f32 v98, v71, v69
	v_min_f32 v69, v71, v69
	v_max_f32 v71, v65, v67
	v_min_f32 v65, v65, v67
	v_min_f32 v68, v70, v68
	v_max_f32 v70, v77, v80
	v_min_f32 v77, v77, v80
	v_max_f32 v97, v79, v73
	v_min_f32 v101, v79, v73
	s_nop 0
	v_max_f32 v75, v96, v76
	v_max_f32 v67, v66, v68
	v_min_f32 v66, v66, v68
	v_max_f32 v80, v70, v95
	v_min_f32 v79, v70, v95
	v_min_f32 v76, v96, v76
	v_max_f32 v78, v77, v81
	v_min_f32 v77, v77, v81
	s_nop 0
	v_max_f32 v95, v65, v66
	v_min_f32 v96, v65, v66
	v_ashrrev_i32_e32 v65, 31, v64
	v_max_f32 v73, v94, v74
	v_min_f32 v74, v94, v74
	v_max_f32 v81, v71, v67
	v_min_f32 v94, v71, v67
	v_lshl_add_u64 v[66:67], s[18:19], 0, v[64:65]
	v_lshlrev_b64 v[66:67], 4, v[66:67]
	v_max_f32 v100, v97, v98
	v_min_f32 v99, v97, v98
	v_max_f32 v98, v101, v69
	v_min_f32 v97, v101, v69
	v_lshlrev_b64 v[68:69], 2, v[66:67]
	s_mov_b64 s[24:25], -1
	s_and_b64 vcc, exec, s[4:5]
	v_lshl_add_u64 v[70:71], s[6:7], 0, v[68:69]
	v_lshl_add_u64 v[68:69], s[8:9], 0, v[68:69]
	s_cbranch_vccz .LBB0_602
	v_lshlrev_b32_e32 v65, 6, v100
	v_lshlrev_b32_e32 v101, 10, v100
	v_lshlrev_b32_e32 v102, 6, v99
	v_lshlrev_b32_e32 v103, 10, v99
	v_lshlrev_b32_e32 v111, 10, v97
	v_and_b32_e32 v65, 0x3c00, v65
	v_and_b32_e32 v101, 0x3c00, v101
	v_and_b32_e32 v102, 0x3c00, v102
	v_and_b32_e32 v103, 0x3c00, v103
	v_lshlrev_b32_e32 v108, 6, v98
	v_lshlrev_b32_e32 v109, 10, v98
	v_lshlrev_b32_e32 v110, 6, v97
	v_and_b32_e32 v111, 0x3c00, v111
	v_add_u32_e32 v65, v82, v65
	v_add_u32_e32 v101, v82, v101
	v_add_u32_e32 v102, v82, v102
	v_add_u32_e32 v103, v82, v103
	v_and_b32_e32 v108, 0x3c00, v108
	v_and_b32_e32 v109, 0x3c00, v109
	v_and_b32_e32 v110, 0x3c00, v110
	v_add_u32_e32 v111, v82, v111
	v_add_u32_e32 v108, v82, v108
	v_add_u32_e32 v109, v82, v109
	v_add_u32_e32 v110, v82, v110
	ds_read_b32 v65, v65
	ds_read_b32 v101, v101 offset:512
	ds_read_b32 v102, v102
	ds_read_b32 v103, v103 offset:512
	ds_read_b32 v112, v108
	ds_read_b32 v113, v109 offset:512
	ds_read_b32 v114, v110
	ds_read_b32 v111, v111 offset:512
	s_waitcnt lgkmcnt(7)
	v_lshlrev_b32_e32 v65, 7, v65
	s_waitcnt lgkmcnt(6)
	v_and_b32_e32 v101, 0x7f, v101
	v_and_b32_e32 v65, 0x3f80, v65
	v_bitop3_b32 v108, v101, s40, v65 bitop3:0x36
	s_waitcnt lgkmcnt(5)
	v_lshlrev_b32_e32 v101, 7, v102
	s_waitcnt lgkmcnt(4)
	v_and_b32_e32 v65, 0x7f, v103
	v_and_b32_e32 v101, 0x3f80, v101
	v_bitop3_b32 v109, v65, s40, v101 bitop3:0x36
	v_and_b32_e32 v101, 0xffffff00, v99
	s_waitcnt lgkmcnt(3)
	v_lshlrev_b32_e32 v99, 7, v112
	s_waitcnt lgkmcnt(2)
	v_and_b32_e32 v65, 0x7f, v113
	v_and_b32_e32 v99, 0x3f80, v99
	v_and_b32_e32 v102, 0xffffff00, v98
	s_waitcnt lgkmcnt(1)
	v_lshlrev_b32_e32 v98, 7, v114
	v_bitop3_b32 v110, v65, s40, v99 bitop3:0x36
	s_waitcnt lgkmcnt(0)
;     __device__ __forceinline__ void fused(f32x4 (&acc)[2][2][4][2], const Unit& u, int wr, int wc, int fr, int fq, PG8_LAS unsigned char* lds, int wid, int lane) const {
;     ...
;                 if (hw == 0) TOPK_EMIT8(0); else TOPK_EMIT8(8);
	v_and_b32_e32 v65, 0x7f, v111
	v_and_b32_e32 v98, 0x3f80, v98
	v_bitop3_b32 v111, v65, s40, v98 bitop3:0x36
	v_and_b32_e32 v103, 0xffffff00, v97
	v_lshlrev_b32_e32 v65, 6, v81
	v_lshlrev_b32_e32 v97, 10, v81
	v_lshlrev_b32_e32 v98, 6, v94
	v_lshlrev_b32_e32 v99, 10, v94
	v_lshlrev_b32_e32 v115, 10, v96
	v_and_b32_e32 v65, 0x3c00, v65
	v_and_b32_e32 v97, 0x3c00, v97
	v_and_b32_e32 v98, 0x3c00, v98
	v_and_b32_e32 v99, 0x3c00, v99
	v_lshlrev_b32_e32 v112, 6, v95
	v_lshlrev_b32_e32 v113, 10, v95
	v_lshlrev_b32_e32 v114, 6, v96
	v_and_b32_e32 v115, 0x3c00, v115
	v_add_u32_e32 v65, v82, v65
	v_add_u32_e32 v97, v82, v97
	v_add_u32_e32 v98, v82, v98
	v_add_u32_e32 v99, v82, v99
	v_and_b32_e32 v112, 0x3c00, v112
	v_and_b32_e32 v113, 0x3c00, v113
	v_and_b32_e32 v114, 0x3c00, v114
	v_add_u32_e32 v115, v82, v115
	v_add_u32_e32 v112, v82, v112
	v_add_u32_e32 v113, v82, v113
	v_add_u32_e32 v114, v82, v114
	ds_read_b32 v65, v65
	ds_read_b32 v97, v97 offset:512
	ds_read_b32 v98, v98
	ds_read_b32 v99, v99 offset:512
	ds_read_b32 v120, v112
	ds_read_b32 v121, v113 offset:512
	ds_read_b32 v122, v114
	ds_read_b32 v115, v115 offset:512
	s_waitcnt lgkmcnt(7)
	v_lshlrev_b32_e32 v65, 7, v65
	s_waitcnt lgkmcnt(6)
	v_and_b32_e32 v97, 0x7f, v97
	v_and_b32_e32 v65, 0x3f80, v65
	v_bitop3_b32 v112, v97, s40, v65 bitop3:0x36
	s_waitcnt lgkmcnt(5)
	v_lshlrev_b32_e32 v97, 7, v98
	s_waitcnt lgkmcnt(4)
	v_and_b32_e32 v65, 0x7f, v99
	v_and_b32_e32 v97, 0x3f80, v97
	v_bitop3_b32 v113, v65, s40, v97 bitop3:0x36
	s_waitcnt lgkmcnt(3)
	v_lshlrev_b32_e32 v97, 7, v120
	s_waitcnt lgkmcnt(2)
	v_and_b32_e32 v65, 0x7f, v121
	v_and_b32_e32 v97, 0x3f80, v97
	v_bitop3_b32 v114, v65, s40, v97 bitop3:0x36
	s_waitcnt lgkmcnt(1)
	v_lshlrev_b32_e32 v97, 7, v122
	s_waitcnt lgkmcnt(0)
	v_and_b32_e32 v65, 0x7f, v115
	v_and_b32_e32 v97, 0x3f80, v97
	v_and_b32_e32 v100, 0xffffff00, v100
	v_bitop3_b32 v115, v65, s40, v97 bitop3:0x36
	global_store_dwordx4 v[70:71], v[108:111], off offset:32 sc0 sc1
	global_store_dwordx4 v[70:71], v[112:115], off offset:48 sc0 sc1
	global_store_dwordx4 v[68:69], v[100:103], off offset:32 sc0 sc1
	s_mov_b64 s[24:25], 0
.LBB0_602:
	s_andn2_b64 vcc, exec, s[24:25]
	s_cbranch_vccnz .LBB0_604
	v_lshlrev_b32_e32 v65, 6, v80
	v_lshlrev_b32_e32 v81, 10, v80
	v_lshlrev_b32_e32 v95, 10, v79
	v_lshlrev_b32_e32 v96, 6, v78
	v_lshlrev_b32_e32 v97, 10, v78
	v_and_b32_e32 v65, 0x3c00, v65
	v_and_b32_e32 v81, 0x3c00, v81
	v_lshlrev_b32_e32 v94, 6, v79
	v_and_b32_e32 v95, 0x3c00, v95
	v_and_b32_e32 v96, 0x3c00, v96
	v_and_b32_e32 v97, 0x3c00, v97
	v_lshlrev_b32_e32 v98, 6, v77
	v_lshlrev_b32_e32 v99, 10, v77
	v_add_u32_e32 v65, v72, v65
	v_add_u32_e32 v81, v72, v81
	v_and_b32_e32 v94, 0x3c00, v94
	v_add_u32_e32 v95, v72, v95
	v_add_u32_e32 v96, v72, v96
	v_add_u32_e32 v97, v72, v97
	v_and_b32_e32 v98, 0x3c00, v98
	v_and_b32_e32 v99, 0x3c00, v99
	v_add_u32_e32 v94, v72, v94
	v_add_u32_e32 v98, v72, v98
	v_add_u32_e32 v99, v72, v99
	ds_read_b32 v65, v65
	ds_read_b32 v81, v81 offset:512
	ds_read_b32 v100, v94
	ds_read_b32 v95, v95 offset:512
	ds_read_b32 v96, v96
	ds_read_b32 v97, v97 offset:512
	ds_read_b32 v101, v98
	ds_read_b32 v102, v99 offset:512
	s_waitcnt lgkmcnt(7)
	v_lshlrev_b32_e32 v65, 7, v65
	s_waitcnt lgkmcnt(6)
	v_and_b32_e32 v81, 0x7f, v81
	v_and_b32_e32 v65, 0x3f80, v65
	v_and_b32_e32 v98, 0xffffff00, v80
	s_waitcnt lgkmcnt(5)
	v_lshlrev_b32_e32 v80, 7, v100
	v_bitop3_b32 v94, v81, s40, v65 bitop3:0x36
	s_waitcnt lgkmcnt(4)
	v_and_b32_e32 v65, 0x7f, v95
	v_and_b32_e32 v80, 0x3f80, v80
	v_and_b32_e32 v99, 0xffffff00, v79
	s_waitcnt lgkmcnt(3)
	v_lshlrev_b32_e32 v79, 7, v96
	v_bitop3_b32 v95, v65, s40, v80 bitop3:0x36
	s_waitcnt lgkmcnt(2)
	v_and_b32_e32 v65, 0x7f, v97
	v_and_b32_e32 v79, 0x3f80, v79
	v_and_b32_e32 v100, 0xffffff00, v78
	s_waitcnt lgkmcnt(1)
	v_lshlrev_b32_e32 v78, 7, v101
	v_bitop3_b32 v96, v65, s40, v79 bitop3:0x36
	s_waitcnt lgkmcnt(0)
	v_and_b32_e32 v65, 0x7f, v102
	v_and_b32_e32 v78, 0x3f80, v78
	v_bitop3_b32 v97, v65, s40, v78 bitop3:0x36
	v_and_b32_e32 v101, 0xffffff00, v77
	v_lshlrev_b32_e32 v65, 6, v73
	v_lshlrev_b32_e32 v77, 10, v73
	v_lshlrev_b32_e32 v79, 10, v74
	v_lshlrev_b32_e32 v80, 6, v75
	v_lshlrev_b32_e32 v81, 10, v75
	v_lshlrev_b32_e32 v102, 6, v76
	v_lshlrev_b32_e32 v103, 10, v76
	v_and_b32_e32 v65, 0x3c00, v65
	v_and_b32_e32 v77, 0x3c00, v77
	v_lshlrev_b32_e32 v78, 6, v74
	v_and_b32_e32 v79, 0x3c00, v79
	v_and_b32_e32 v80, 0x3c00, v80
	v_and_b32_e32 v81, 0x3c00, v81
	v_and_b32_e32 v102, 0x3c00, v102
	v_and_b32_e32 v103, 0x3c00, v103
	v_add_u32_e32 v65, v72, v65
	v_add_u32_e32 v77, v72, v77
	v_and_b32_e32 v78, 0x3c00, v78
	v_add_u32_e32 v79, v72, v79
	v_add_u32_e32 v80, v72, v80
	v_add_u32_e32 v81, v72, v81
	v_add_u32_e32 v102, v72, v102
	v_add_u32_e32 v103, v72, v103
	v_add_u32_e32 v78, v72, v78
	ds_read_b32 v65, v65
	ds_read_b32 v77, v77 offset:512
	ds_read_b32 v108, v78
	ds_read_b32 v79, v79 offset:512
	ds_read_b32 v80, v80
	ds_read_b32 v81, v81 offset:512
	ds_read_b32 v102, v102
	ds_read_b32 v103, v103 offset:512
	s_waitcnt lgkmcnt(7)
	v_lshlrev_b32_e32 v65, 7, v65
	s_waitcnt lgkmcnt(6)
	v_and_b32_e32 v77, 0x7f, v77
	v_and_b32_e32 v65, 0x3f80, v65
	v_bitop3_b32 v78, v77, s40, v65 bitop3:0x36
	s_waitcnt lgkmcnt(5)
	v_lshlrev_b32_e32 v77, 7, v108
	s_waitcnt lgkmcnt(4)
	v_and_b32_e32 v65, 0x7f, v79
	v_and_b32_e32 v77, 0x3f80, v77
	v_bitop3_b32 v79, v65, s40, v77 bitop3:0x36
	s_waitcnt lgkmcnt(3)
	v_lshlrev_b32_e32 v77, 7, v80
	s_waitcnt lgkmcnt(2)
	v_and_b32_e32 v65, 0x7f, v81
	v_and_b32_e32 v77, 0x3f80, v77
	v_bitop3_b32 v80, v65, s40, v77 bitop3:0x36
	s_waitcnt lgkmcnt(1)
	v_lshlrev_b32_e32 v77, 7, v102
	s_waitcnt lgkmcnt(0)
	v_and_b32_e32 v65, 0x7f, v103
	v_and_b32_e32 v77, 0x3f80, v77
	v_bitop3_b32 v81, v65, s40, v77 bitop3:0x36
	global_store_dwordx4 v[70:71], v[94:97], off sc0 sc1
	global_store_dwordx4 v[70:71], v[78:81], off offset:16 sc0 sc1
	global_store_dwordx4 v[68:69], v[98:101], off sc0 sc1
	s_mov_b64 s[24:25], 16
	v_mov_b32_e32 v81, v73
	v_mov_b32_e32 v94, v74
	v_mov_b32_e32 v95, v75
	v_mov_b32_e32 v96, v76
	s_branch .LBB0_605

.LBB0_605:
	v_lshl_add_u64 v[66:67], v[66:67], 2, s[8:9]
	v_and_b32_e32 v71, 0xffffff00, v96
	v_and_b32_e32 v70, 0xffffff00, v95
	v_and_b32_e32 v69, 0xffffff00, v94
	v_and_b32_e32 v68, 0xffffff00, v81
	v_lshl_add_u64 v[66:67], v[66:67], 0, s[24:25]
	global_store_dwordx4 v[66:67], v[68:71], off sc0 sc1

; #define PG8_LAS __attribute__((address_space(3)))
;     __device__ __forceinline__ void fused(f32x4 (&acc)[2][2][4][2], const Unit& u, int wr, int wc, int fr, int fq, PG8_LAS unsigned char* lds, int wid, int lane) const {
;     ...
;             __syncthreads();
;             if (tid < 256) {
;                 const int row = tid & 127, hw = tid >> 7;
;                 PG8_LAS const unsigned* l2 = (PG8_LAS const unsigned*)lds;
;                 unsigned T[16], G[16];
; #pragma unroll
;                 for (int i = 0; i < 16; ++i) { T[i] = l2[i * 128 + row]; G[i] = l2[(16 + i) * 128 + row]; }
;                 merge16_desc(T, G);
;                 const size_t o = ((size_t)h * M + (size_t)(u.pm * BM + ai * HALF + row)) * 16;
;     ...
;                 if (hw == 0) TOPK_EMIT8(0); else TOPK_EMIT8(8);
.LBB0_616:
	s_or_b64 exec, exec, s[22:23]
	s_waitcnt lgkmcnt(0)
	s_barrier
	s_and_saveexec_b64 s[22:23], s[0:1]
	s_cbranch_execz .LBB0_578
	ds_read2st64_b32 v[0:1], v83 offset1:2
	ds_read2st64_b32 v[2:3], v83 offset0:32 offset1:34
	ds_read2st64_b32 v[4:5], v83 offset0:4 offset1:6
	ds_read2st64_b32 v[6:7], v83 offset0:36 offset1:38
	ds_read2st64_b32 v[8:9], v83 offset0:8 offset1:10
	ds_read2st64_b32 v[10:11], v83 offset0:40 offset1:42
	ds_read2st64_b32 v[12:13], v83 offset0:12 offset1:14
	ds_read2st64_b32 v[14:15], v83 offset0:44 offset1:46
	ds_read2st64_b32 v[16:17], v83 offset0:16 offset1:18
	ds_read2st64_b32 v[18:19], v83 offset0:48 offset1:50
	ds_read2st64_b32 v[20:21], v83 offset0:20 offset1:22
	ds_read2st64_b32 v[22:23], v83 offset0:60 offset1:62
	ds_read2st64_b32 v[24:25], v83 offset0:52 offset1:54
	ds_read2st64_b32 v[26:27], v83 offset0:56 offset1:58
	ds_read2st64_b32 v[28:29], v83 offset0:24 offset1:26
	ds_read2st64_b32 v[30:31], v83 offset0:28 offset1:30
	s_waitcnt lgkmcnt(4)
	v_max_f32 v0, v0, v23
	v_max_f32 v1, v1, v22
	s_waitcnt lgkmcnt(2)
	v_max_f32 v4, v4, v27
	v_max_f32 v5, v5, v26
	v_max_f32 v8, v8, v25
	v_max_f32 v9, v9, v24
	v_max_f32 v12, v12, v19
	v_max_f32 v15, v16, v15
	v_max_f32 v14, v17, v14
	v_max_f32 v11, v20, v11
	v_max_f32 v10, v21, v10
	s_waitcnt lgkmcnt(1)
	v_max_f32 v7, v28, v7
	v_max_f32 v6, v29, v6
	s_waitcnt lgkmcnt(0)
	v_max_f32 v3, v30, v3
	v_max_f32 v13, v13, v18
	v_max_f32 v2, v31, v2
	v_max_f32 v16, v0, v15
	v_min_f32 v0, v0, v15
	v_max_f32 v15, v1, v14
	v_min_f32 v1, v1, v14
	v_max_f32 v14, v4, v11
	v_min_f32 v4, v4, v11
	v_max_f32 v11, v5, v10
	v_min_f32 v5, v5, v10
	v_max_f32 v10, v8, v7
	v_min_f32 v7, v8, v7
	v_max_f32 v8, v9, v6
	v_min_f32 v6, v9, v6
	s_nop 0
	v_max_f32 v9, v12, v3
	v_min_f32 v3, v12, v3
	v_max_f32 v12, v13, v2
	v_min_f32 v2, v13, v2
	v_max_f32 v13, v16, v10
	v_min_f32 v10, v16, v10
	v_max_f32 v16, v15, v8
	v_min_f32 v8, v15, v8
	s_nop 0
	v_max_f32 v15, v14, v9
	v_min_f32 v9, v14, v9
	v_max_f32 v14, v11, v12
	v_min_f32 v11, v11, v12
	v_max_f32 v12, v0, v7
	v_min_f32 v0, v0, v7
	v_max_f32 v7, v1, v6
	v_min_f32 v1, v1, v6
	v_max_f32 v6, v4, v3
	v_min_f32 v3, v4, v3
	v_max_f32 v4, v5, v2
	s_nop 0
	v_max_f32 v17, v16, v14
	v_min_f32 v14, v16, v14
	v_max_f32 v16, v10, v9
	v_min_f32 v2, v5, v2
	v_max_f32 v24, v0, v3
	v_min_f32 v0, v0, v3
	v_max_f32 v5, v13, v15
	v_min_f32 v15, v13, v15
	v_max_f32 v18, v8, v11
	v_max_f32 v20, v12, v6
	v_min_f32 v22, v12, v6
	v_max_f32 v23, v7, v4
	v_min_f32 v4, v7, v4
	s_nop 0
	v_max_f32 v3, v1, v2
	v_min_f32 v1, v1, v2
	v_max_f32 v13, v5, v17
	v_min_f32 v12, v5, v17
	v_max_f32 v6, v16, v18
	v_min_f32 v7, v16, v18
	v_min_f32 v9, v10, v9
	s_nop 0
	v_max_f32 v16, v0, v1
	v_min_f32 v17, v0, v1
	v_or_b32_e32 v0, 0x80, v64
	v_ashrrev_i32_e32 v1, 31, v0
	v_lshl_add_u64 v[0:1], s[18:19], 0, v[0:1]
	v_lshlrev_b64 v[0:1], 4, v[0:1]
	v_min_f32 v19, v8, v11
	v_max_f32 v11, v15, v14
	v_min_f32 v10, v15, v14
	v_max_f32 v14, v24, v3
	v_min_f32 v15, v24, v3
	v_lshlrev_b64 v[2:3], 2, v[0:1]
	v_max_f32 v8, v9, v19
	v_min_f32 v9, v9, v19
	v_max_f32 v19, v22, v4
	v_min_f32 v18, v22, v4
	s_mov_b64 s[0:1], -1
	s_and_b64 vcc, exec, s[4:5]
	v_lshl_add_u64 v[4:5], s[6:7], 0, v[2:3]
	v_lshl_add_u64 v[2:3], s[8:9], 0, v[2:3]
	v_max_f32 v21, v20, v23
	v_min_f32 v20, v20, v23
	s_cbranch_vccnz .LBB0_619
	v_lshlrev_b32_e32 v22, 6, v21
	v_lshlrev_b32_e32 v23, 10, v21
	v_lshlrev_b32_e32 v24, 6, v20
	v_lshlrev_b32_e32 v25, 10, v20
	v_lshlrev_b32_e32 v29, 10, v18
	v_and_b32_e32 v22, 0x3c00, v22
	v_and_b32_e32 v23, 0x3c00, v23
	v_and_b32_e32 v24, 0x3c00, v24
	v_and_b32_e32 v25, 0x3c00, v25
	v_lshlrev_b32_e32 v26, 6, v19
	v_lshlrev_b32_e32 v27, 10, v19
	v_lshlrev_b32_e32 v28, 6, v18
	v_and_b32_e32 v29, 0x3c00, v29
	v_add_u32_e32 v22, v82, v22
	v_add_u32_e32 v23, v82, v23
	v_add_u32_e32 v24, v82, v24
	v_add_u32_e32 v25, v82, v25
	v_and_b32_e32 v26, 0x3c00, v26
	v_and_b32_e32 v27, 0x3c00, v27
	v_and_b32_e32 v28, 0x3c00, v28
	v_add_u32_e32 v29, v82, v29
	v_add_u32_e32 v26, v82, v26
	v_add_u32_e32 v27, v82, v27
	v_add_u32_e32 v28, v82, v28
	ds_read_b32 v22, v22
	ds_read_b32 v23, v23 offset:512
	ds_read_b32 v24, v24
	ds_read_b32 v25, v25 offset:512
	ds_read_b32 v30, v26
	ds_read_b32 v31, v27 offset:512
	ds_read_b32 v32, v28
	ds_read_b32 v29, v29 offset:512
	s_waitcnt lgkmcnt(7)
	v_lshlrev_b32_e32 v22, 7, v22
	s_waitcnt lgkmcnt(6)
	v_and_b32_e32 v23, 0x7f, v23
	v_and_b32_e32 v22, 0x3f80, v22
	v_bitop3_b32 v22, v23, s40, v22 bitop3:0x36
	s_waitcnt lgkmcnt(5)
	v_lshlrev_b32_e32 v23, 7, v24
	v_and_b32_e32 v26, 0xffffff00, v21
	s_waitcnt lgkmcnt(4)
	v_and_b32_e32 v21, 0x7f, v25
	v_and_b32_e32 v23, 0x3f80, v23
	v_bitop3_b32 v23, v21, s40, v23 bitop3:0x36
	s_waitcnt lgkmcnt(3)
	v_lshlrev_b32_e32 v21, 7, v30
	v_and_b32_e32 v27, 0xffffff00, v20
	s_waitcnt lgkmcnt(2)
	v_and_b32_e32 v20, 0x7f, v31
	v_and_b32_e32 v21, 0x3f80, v21
	v_bitop3_b32 v24, v20, s40, v21 bitop3:0x36
	s_waitcnt lgkmcnt(1)
	v_lshlrev_b32_e32 v20, 7, v32
	v_and_b32_e32 v28, 0xffffff00, v19
	s_waitcnt lgkmcnt(0)
	v_and_b32_e32 v19, 0x7f, v29
	v_and_b32_e32 v20, 0x3f80, v20
	v_bitop3_b32 v25, v19, s40, v20 bitop3:0x36
	v_and_b32_e32 v29, 0xffffff00, v18
	v_lshlrev_b32_e32 v18, 6, v14
	v_lshlrev_b32_e32 v19, 10, v14
	v_lshlrev_b32_e32 v20, 6, v15
	v_lshlrev_b32_e32 v21, 10, v15
	v_lshlrev_b32_e32 v30, 6, v16
	v_lshlrev_b32_e32 v31, 10, v16
	v_lshlrev_b32_e32 v32, 6, v17
	v_lshlrev_b32_e32 v33, 10, v17
	v_and_b32_e32 v18, 0x3c00, v18
	v_and_b32_e32 v19, 0x3c00, v19
	v_and_b32_e32 v20, 0x3c00, v20
	v_and_b32_e32 v21, 0x3c00, v21
	v_and_b32_e32 v30, 0x3c00, v30
	v_and_b32_e32 v31, 0x3c00, v31
	v_and_b32_e32 v32, 0x3c00, v32
	v_and_b32_e32 v33, 0x3c00, v33
	v_add_u32_e32 v18, v82, v18
	v_add_u32_e32 v19, v82, v19
	v_add_u32_e32 v20, v82, v20
	v_add_u32_e32 v21, v82, v21
	v_add_u32_e32 v30, v82, v30
	v_add_u32_e32 v31, v82, v31
	v_add_u32_e32 v32, v82, v32
	v_add_u32_e32 v33, v82, v33
	ds_read_b32 v18, v18
	ds_read_b32 v19, v19 offset:512
	ds_read_b32 v20, v20
	ds_read_b32 v21, v21 offset:512
	ds_read_b32 v30, v30
	ds_read_b32 v31, v31 offset:512
	ds_read_b32 v32, v32
	ds_read_b32 v33, v33 offset:512
	s_waitcnt lgkmcnt(7)
	v_lshlrev_b32_e32 v18, 7, v18
	s_waitcnt lgkmcnt(6)
	v_and_b32_e32 v19, 0x7f, v19
	v_and_b32_e32 v18, 0x3f80, v18
	s_waitcnt lgkmcnt(5)
	v_lshlrev_b32_e32 v20, 7, v20
	v_bitop3_b32 v18, v19, s40, v18 bitop3:0x36
	s_waitcnt lgkmcnt(4)
	v_and_b32_e32 v19, 0x7f, v21
	v_and_b32_e32 v20, 0x3f80, v20
	s_waitcnt lgkmcnt(3)
	v_lshlrev_b32_e32 v21, 7, v30
	v_bitop3_b32 v19, v19, s40, v20 bitop3:0x36
	s_waitcnt lgkmcnt(2)
	v_and_b32_e32 v20, 0x7f, v31
	v_and_b32_e32 v21, 0x3f80, v21
	s_waitcnt lgkmcnt(1)
	v_lshlrev_b32_e32 v30, 7, v32
	v_bitop3_b32 v20, v20, s40, v21 bitop3:0x36
	s_waitcnt lgkmcnt(0)
	v_and_b32_e32 v21, 0x7f, v33
	v_and_b32_e32 v30, 0x3f80, v30
	s_mov_b64 s[0:1], 0
	v_bitop3_b32 v21, v21, s40, v30 bitop3:0x36
	global_store_dwordx4 v[4:5], v[22:25], off offset:32 sc0 sc1
	global_store_dwordx4 v[4:5], v[18:21], off offset:48 sc0 sc1
	global_store_dwordx4 v[2:3], v[26:29], off offset:32 sc0 sc1
